# ret1: first-load consumers moved below the remaining row loads (one round trip instead of two); EpiOutFused: per-column factor loads no longer drain the residual prefetch
# baseline (speedup 1.0000x reference)
.LBB0_646:
	s_andn2_b64 vcc, exec, s[6:7]
	s_mov_b32 s94, s18
	s_cbranch_vccnz .LBB0_648
	s_lshl_b32 s6, s12, 1
	s_add_i32 s0, s6, 0xfbe0
	s_and_b32 s7, s0, 0xfffe
	s_mul_i32 s7, s7, 0xf0f1
	s_lshr_b32 s7, s7, 21
	s_mul_i32 s7, s7, 34
	s_sub_i32 s0, s0, s7
	s_and_b32 s0, s0, 0xfffe
	s_lshl_b32 s7, s0, 7
	s_cmp_eq_u32 s0, 0
	s_movk_i32 s16, 0xff00
	s_movk_i32 s17, 0x300
	s_cselect_b32 s8, 0x4000, s16
	s_cselect_b32 s9, s17, 0x3000
	s_add_i32 s6, s6, 0xfbe1
	s_add_i32 s13, s8, s7
	s_and_b32 s7, s6, 0xffff
	s_mul_i32 s7, s7, 0xf0f1
	s_lshr_b32 s7, s7, 21
	s_mul_i32 s7, s7, 34
	s_sub_i32 s6, s6, s7
	s_and_b32 s8, s6, 0xffff
	s_add_i32 s13, s13, s9
	s_lshl_b32 s6, s8, 7
	s_cmp_eq_u32 s8, 1
	s_cselect_b32 s7, 0x4000, s16
	s_cselect_b32 s9, s17, 0x3000
	s_add_i32 s6, s7, s6
	s_add_i32 s9, s6, s9
	s_lshl_b32 s6, s5, 3
	s_ashr_i32 s7, s6, 31
	s_lshl_b64 s[6:7], s[6:7], 2
	s_add_u32 s6, s42, s6
	s_addc_u32 s7, s43, s7
	global_load_dword v0, v33, s[6:7] offset:12
	global_load_dword v1, v33, s[6:7] offset:28
	s_mov_b32 s6, 0xbfb8aa3b
	s_mov_b32 s16, 0x3f317218
	s_mov_b32 s7, 0x7f800000
	s_mov_b32 s17, 0x33800000
	v_ashrrev_i32_e32 v31, 3, v206
	v_readlane_b32 s20, v254, 56
	v_readlane_b32 s21, v254, 57
	v_and_b32_e32 v16, 15, v206
	v_lshlrev_b32_e32 v102, 2, v16
	v_and_b32_e32 v86, 12, v102
	v_mov_b32_e32 v62, 0x1400
	v_mov_b32_e32 v80, 0x1e00
	s_mov_b32 s94, 2
	s_waitcnt vmcnt(1)
	v_mul_f32_e32 v2, 0xbfb8aa3b, v0
	s_waitcnt vmcnt(0)
	v_mul_f32_e32 v3, 0xbfb8aa3b, v1
	v_fma_f32 v4, v0, s6, -v2
	v_rndne_f32_e32 v5, v2
	v_fma_f32 v6, v1, s6, -v3
	v_rndne_f32_e32 v7, v3
	v_fmac_f32_e32 v4, 0xb2a5705f, v0
	v_sub_f32_e32 v2, v2, v5
	v_fmac_f32_e32 v6, 0xb2a5705f, v1
	v_sub_f32_e32 v3, v3, v7
	v_add_f32_e32 v2, v2, v4
	v_cvt_i32_f32_e32 v5, v5
	v_add_f32_e32 v3, v3, v6
	v_exp_f32_e32 v2, v2
	v_cvt_i32_f32_e32 v7, v7
	v_exp_f32_e32 v3, v3
	s_mov_b32 s6, 0x42ce8ed0
	v_ldexp_f32 v2, v2, v5
	v_cmp_nlt_f32_e32 vcc, s6, v0
	v_ldexp_f32 v3, v3, v7
	s_nop 0
	v_cndmask_b32_e32 v2, 0, v2, vcc
	v_cmp_nlt_f32_e32 vcc, s6, v1
	s_mov_b32 s6, 0xc2b17218
	s_nop 0
	v_cndmask_b32_e32 v3, 0, v3, vcc
	v_cmp_ngt_f32_e32 vcc, s6, v0
	s_nop 1
	v_cndmask_b32_e32 v17, v227, v2, vcc
	v_cmp_ngt_f32_e32 vcc, s6, v1
	v_add_f32_e32 v1, 1.0, v17
	v_frexp_mant_f32_e32 v7, v1
	v_cndmask_b32_e32 v0, v227, v3, vcc
	v_cvt_f64_f32_e32 v[2:3], v1
	s_mov_b32 s6, 0x3f2aaaab
	v_add_f32_e32 v20, 1.0, v0
	v_add_f32_e32 v6, -1.0, v1
	v_frexp_exp_i32_f64_e32 v2, v[2:3]
	v_cmp_gt_f32_e32 vcc, s6, v7
	v_add_f32_e32 v8, -1.0, v20
	v_cvt_f64_f32_e32 v[4:5], v20
	v_sub_f32_e32 v9, v6, v1
	v_subbrev_co_u32_e32 v2, vcc, 0, v2, vcc
	v_sub_f32_e32 v6, v17, v6
	v_sub_f32_e32 v3, v8, v20
	v_frexp_exp_i32_f64_e32 v22, v[4:5]
	v_add_f32_e32 v4, 1.0, v9
	v_sub_u32_e32 v5, 0, v2
	v_sub_f32_e32 v8, v0, v8
	v_add_f32_e32 v3, 1.0, v3
	v_add_f32_e32 v4, v6, v4
	v_ldexp_f32 v1, v1, v5
	v_add_f32_e32 v23, v8, v3
	v_ldexp_f32 v3, v4, v5
	v_add_f32_e32 v4, -1.0, v1
	v_add_f32_e32 v6, 1.0, v1
	v_add_f32_e32 v5, 1.0, v4
	v_add_f32_e32 v7, -1.0, v6
	v_sub_f32_e32 v5, v1, v5
	v_sub_f32_e32 v1, v1, v7
	v_add_f32_e32 v1, v3, v1
	v_add_f32_e32 v7, v3, v5
	v_add_f32_e32 v3, v6, v1
	v_rcp_f32_e32 v10, v3
	v_add_f32_e32 v5, v4, v7
	v_sub_f32_e32 v6, v6, v3
	v_add_f32_e32 v1, v1, v6
	v_mul_f32_e32 v12, v5, v10
	v_mul_f32_e32 v6, v3, v12
	v_fma_f32 v8, v12, v3, -v6
	v_sub_f32_e32 v4, v4, v5
	v_fmac_f32_e32 v8, v12, v1
	v_add_f32_e32 v11, v7, v4
	v_add_f32_e32 v4, v6, v8
	v_sub_f32_e32 v7, v5, v4
	v_mov_b32_e32 v9, v4
	v_pk_add_f32 v[4:5], v[4:5], v[6:7] neg_lo:[0,1] neg_hi:[0,1]
	v_cvt_f32_i32_e32 v2, v2
	v_pk_add_f32 v[4:5], v[4:5], v[8:9] neg_lo:[0,1] neg_hi:[0,1]
	v_cmp_neq_f32_e32 vcc, s7, v17
	v_add_f32_e32 v5, v11, v5
	v_add_f32_e32 v4, v4, v5
	v_add_f32_e32 v5, v7, v4
	v_mul_f32_e32 v9, v10, v5
	v_mul_f32_e32 v6, v3, v9
	v_fma_f32 v8, v9, v3, -v6
	v_sub_f32_e32 v7, v7, v5
	v_fmac_f32_e32 v8, v9, v1
	v_add_f32_e32 v11, v4, v7
	v_add_f32_e32 v13, v12, v9
	v_add_f32_e32 v4, v6, v8
	v_sub_f32_e32 v3, v13, v12
	v_sub_f32_e32 v7, v5, v4
	v_sub_f32_e32 v1, v9, v3
	v_mov_b32_e32 v9, v4
	v_pk_add_f32 v[4:5], v[4:5], v[6:7] neg_lo:[0,1] neg_hi:[0,1]
	v_frexp_mant_f32_e32 v21, v20
	v_pk_add_f32 v[4:5], v[4:5], v[8:9] neg_lo:[0,1] neg_hi:[0,1]
	s_nop 0
	v_add_f32_e32 v3, v11, v5
	v_add_f32_e32 v3, v4, v3
	v_add_f32_e32 v3, v7, v3
	v_mul_f32_e32 v3, v10, v3
	v_add_f32_e32 v1, v1, v3
	v_add_f32_e32 v3, v13, v1
	v_mul_f32_e32 v4, v3, v3
	v_fmamk_f32 v7, v4, 0x3e9b6dac, v252
	v_sub_f32_e32 v6, v3, v13
	v_ldexp_f32 v5, v3, 1
	v_mul_f32_e32 v3, v3, v4
	v_fmaak_f32 v201, v4, v7, 0x3f2aaada
	v_sub_f32_e32 v1, v1, v6
	v_pk_mul_f32 v[6:7], v[2:3], v[200:201]
	v_ldexp_f32 v1, v1, 1
	v_fma_f32 v4, v2, s16, -v6
	v_fmac_f32_e32 v4, 0xb102e308, v2
	v_pk_add_f32 v[2:3], v[6:7], v[4:5]
	v_mov_b32_e32 v8, v6
	v_sub_f32_e32 v9, v3, v5
	v_pk_add_f32 v[10:11], v[2:3], v[6:7] neg_lo:[0,1] neg_hi:[0,1]
	v_sub_f32_e32 v7, v7, v9
	v_add_f32_e32 v9, v1, v7
	v_pk_add_f32 v[14:15], v[2:3], v[8:9]
	v_mov_b32_e32 v5, v2
	v_mov_b32_e32 v11, v15
	v_pk_add_f32 v[18:19], v[4:5], v[10:11] neg_lo:[0,1] neg_hi:[0,1]
	v_pk_add_f32 v[4:5], v[4:5], v[10:11]
	v_mov_b32_e32 v6, v3
	v_mov_b32_e32 v13, v2
	v_pk_add_f32 v[2:3], v[4:5], v[2:3] op_sel:[1,0] op_sel_hi:[0,1] neg_lo:[0,1] neg_hi:[0,1]
	v_mov_b32_e32 v12, v9
	v_mov_b32_e32 v8, v15
	v_mov_b32_e32 v9, v5
	v_mov_b32_e32 v7, v2
	v_pk_add_f32 v[10:11], v[14:15], v[2:3] op_sel_hi:[1,0] neg_lo:[0,1] neg_hi:[0,1]
	v_pk_add_f32 v[2:3], v[8:9], v[6:7] neg_lo:[0,1] neg_hi:[0,1]
	v_mov_b32_e32 v10, v18
	v_pk_add_f32 v[2:3], v[12:13], v[2:3] neg_lo:[0,1] neg_hi:[0,1]
	v_mov_b32_e32 v19, v5
	v_pk_add_f32 v[6:7], v[10:11], v[2:3]
	s_nop 0
	v_pk_add_f32 v[8:9], v[6:7], v[6:7] op_sel:[0,1] op_sel_hi:[1,0]
	s_nop 0
	v_pk_add_f32 v[4:5], v[4:5], v[8:9] op_sel:[1,0] op_sel_hi:[0,1]
	v_mov_b32_e32 v7, v4
	v_mov_b32_e32 v3, v8
	v_pk_add_f32 v[8:9], v[6:7], v[18:19] neg_lo:[0,1] neg_hi:[0,1]
	s_nop 0
	v_sub_f32_e32 v1, v6, v8
	v_pk_add_f32 v[2:3], v[2:3], v[8:9] neg_lo:[0,1] neg_hi:[0,1]
	v_sub_f32_e32 v1, v18, v1
	v_add_f32_e32 v1, v2, v1
	v_add_f32_e32 v1, v1, v3
	v_add_f32_e32 v1, v4, v1
	v_cndmask_b32_e32 v1, v227, v1, vcc
	v_cmp_lt_f32_e64 vcc, |v17|, s17
	s_nop 1
	v_cndmask_b32_e32 v17, v1, v17, vcc
	v_cmp_gt_f32_e32 vcc, s6, v21
	s_movk_i32 s6, 0x1000
	s_nop 0
	v_subbrev_co_u32_e32 v1, vcc, 0, v22, vcc
	v_sub_u32_e32 v2, 0, v1
	v_ldexp_f32 v3, v20, v2
	v_add_f32_e32 v4, -1.0, v3
	v_add_f32_e32 v6, 1.0, v3
	v_add_f32_e32 v5, 1.0, v4
	v_add_f32_e32 v7, -1.0, v6
	v_ldexp_f32 v2, v23, v2
	v_sub_f32_e32 v5, v3, v5
	v_sub_f32_e32 v3, v3, v7
	v_add_f32_e32 v5, v2, v5
	v_add_f32_e32 v2, v2, v3
	v_add_f32_e32 v10, v6, v2
	v_rcp_f32_e32 v12, v10
	v_sub_f32_e32 v3, v6, v10
	v_add_f32_e32 v11, v2, v3
	v_add_f32_e32 v3, v4, v5
	v_mul_f32_e32 v14, v3, v12
	v_sub_f32_e32 v2, v4, v3
	v_mul_f32_e32 v4, v10, v14
	v_fma_f32 v6, v14, v10, -v4
	v_fmac_f32_e32 v6, v14, v11
	v_add_f32_e32 v13, v5, v2
	v_add_f32_e32 v2, v4, v6
	v_sub_f32_e32 v5, v3, v2
	v_pk_add_f32 v[8:9], v[2:3], v[4:5] neg_lo:[0,1] neg_hi:[0,1]
	v_mov_b32_e32 v7, v2
	v_pk_add_f32 v[2:3], v[8:9], v[6:7] neg_lo:[0,1] neg_hi:[0,1]
	s_nop 0
	v_add_f32_e32 v3, v13, v3
	v_add_f32_e32 v2, v2, v3
	v_add_f32_e32 v3, v5, v2
	v_mul_f32_e32 v13, v12, v3
	v_mul_f32_e32 v4, v10, v13
	v_fma_f32 v6, v13, v10, -v4
	v_fmac_f32_e32 v6, v13, v11
	v_sub_f32_e32 v5, v5, v3
	v_add_f32_e32 v10, v2, v5
	v_add_f32_e32 v2, v4, v6
	v_sub_f32_e32 v5, v3, v2
	v_pk_add_f32 v[8:9], v[2:3], v[4:5] neg_lo:[0,1] neg_hi:[0,1]
	v_mov_b32_e32 v7, v2
	v_pk_add_f32 v[2:3], v[8:9], v[6:7] neg_lo:[0,1] neg_hi:[0,1]
	s_nop 0
	v_add_f32_e32 v3, v10, v3
	v_add_f32_e32 v2, v2, v3
	v_add_f32_e32 v3, v14, v13
	v_add_f32_e32 v2, v5, v2
	v_sub_f32_e32 v4, v3, v14
	v_mul_f32_e32 v2, v12, v2
	v_sub_f32_e32 v4, v13, v4
	v_add_f32_e32 v4, v4, v2
	v_add_f32_e32 v6, v3, v4
	v_mul_f32_e32 v7, v6, v6
	v_fmamk_f32 v2, v7, 0x3e9b6dac, v252
	v_fmaak_f32 v201, v7, v2, 0x3f2aaada
	v_cvt_f32_i32_e32 v2, v1
	v_sub_f32_e32 v1, v6, v3
	v_mul_f32_e32 v3, v6, v7
	v_ldexp_f32 v5, v6, 1
	v_pk_mul_f32 v[6:7], v[2:3], v[200:201]
	v_sub_f32_e32 v1, v4, v1
	v_fma_f32 v4, v2, s16, -v6
	v_fmac_f32_e32 v4, 0xb102e308, v2
	v_pk_add_f32 v[2:3], v[6:7], v[4:5]
	v_ldexp_f32 v1, v1, 1
	v_sub_f32_e32 v5, v3, v5
	v_sub_f32_e32 v5, v7, v5
	v_add_f32_e32 v9, v1, v5
	v_lshlrev_b32_e32 v1, 3, v206
	v_and_b32_e32 v30, 56, v1
	v_add_u32_e32 v12, s13, v31
	v_mov_b32_e32 v8, v6
	v_lshlrev_b32_e32 v32, 1, v30
	v_ashrrev_i32_e32 v13, 31, v12
	v_pk_add_f32 v[6:7], v[2:3], v[6:7] neg_lo:[0,1] neg_hi:[0,1]
	v_pk_add_f32 v[10:11], v[2:3], v[8:9]
	v_lshl_add_u64 v[34:35], s[20:21], 0, v[32:33]
	v_lshlrev_b64 v[12:13], 13, v[12:13]
	v_lshl_add_u64 v[12:13], v[34:35], 0, v[12:13]
	v_mov_b32_e32 v7, v11
	v_mov_b32_e32 v5, v2
	v_add_co_u32_e32 v12, vcc, s6, v12
	v_pk_add_f32 v[14:15], v[4:5], v[6:7] neg_lo:[0,1] neg_hi:[0,1]
	v_pk_add_f32 v[4:5], v[4:5], v[6:7]
	v_addc_co_u32_e32 v13, vcc, 0, v13, vcc
	v_pk_add_f32 v[6:7], v[4:5], v[2:3] op_sel:[1,0] op_sel_hi:[0,1] neg_lo:[0,1] neg_hi:[0,1]
	global_load_dwordx4 v[18:21], v[12:13], off offset:1024
	v_pk_add_f32 v[22:23], v[10:11], v[6:7] op_sel_hi:[1,0] neg_lo:[0,1] neg_hi:[0,1]
	v_mov_b32_e32 v10, v11
	v_mov_b32_e32 v11, v5
	v_mov_b32_e32 v24, v3
	v_mov_b32_e32 v25, v6
	v_pk_add_f32 v[6:7], v[10:11], v[24:25] neg_lo:[0,1] neg_hi:[0,1]
	v_mov_b32_e32 v8, v9
	v_mov_b32_e32 v9, v2
	v_pk_add_f32 v[2:3], v[8:9], v[6:7] neg_lo:[0,1] neg_hi:[0,1]
	v_mov_b32_e32 v22, v14
	v_pk_add_f32 v[6:7], v[22:23], v[2:3]
	v_mov_b32_e32 v15, v5
	v_pk_add_f32 v[8:9], v[6:7], v[6:7] op_sel:[0,1] op_sel_hi:[1,0]
	v_cmp_neq_f32_e32 vcc, s7, v0
	v_pk_add_f32 v[4:5], v[4:5], v[8:9] op_sel:[1,0] op_sel_hi:[0,1]
	v_mov_b32_e32 v7, v4
	v_pk_add_f32 v[10:11], v[6:7], v[14:15] neg_lo:[0,1] neg_hi:[0,1]
	v_mov_b32_e32 v3, v8
	v_sub_f32_e32 v1, v6, v10
	v_pk_add_f32 v[2:3], v[2:3], v[10:11] neg_lo:[0,1] neg_hi:[0,1]
	v_sub_f32_e32 v1, v14, v1
	v_add_f32_e32 v1, v2, v1
	v_add_f32_e32 v1, v1, v3
	v_add_f32_e32 v1, v4, v1
	v_cndmask_b32_e32 v1, v227, v1, vcc
	v_cmp_lt_f32_e64 vcc, |v0|, s17
	global_load_dwordx4 v[22:25], v[12:13], off offset:1536
	v_cndmask_b32_e32 v32, v1, v0, vcc
	v_add_u32_e32 v0, 0x200, v206
	v_ashrrev_i32_e32 v37, 3, v0
	v_add_u32_e32 v0, s13, v37
	v_ashrrev_i32_e32 v1, 31, v0
	v_lshlrev_b64 v[0:1], 13, v[0:1]
	v_lshl_add_u64 v[0:1], v[34:35], 0, v[0:1]
	v_add_co_u32_e32 v0, vcc, s6, v0
	s_nop 0
	v_addc_co_u32_e32 v1, vcc, 0, v1, vcc
	global_load_dwordx4 v[26:29], v[0:1], off offset:1024
	global_load_dwordx4 v[38:41], v[0:1], off offset:1536
	v_add_u32_e32 v0, s9, v31
	v_ashrrev_i32_e32 v1, 31, v0
	v_lshlrev_b64 v[0:1], 13, v[0:1]
	v_lshl_add_u64 v[0:1], v[34:35], 0, v[0:1]
	v_add_co_u32_e32 v0, vcc, s6, v0
	s_nop 0
	v_addc_co_u32_e32 v1, vcc, 0, v1, vcc
	global_load_dwordx4 v[12:15], v[0:1], off offset:1024
	global_load_dwordx4 v[8:11], v[0:1], off offset:1536
	v_add_u32_e32 v0, s9, v37
	v_ashrrev_i32_e32 v1, 31, v0
	v_lshlrev_b64 v[0:1], 13, v[0:1]
	v_lshl_add_u64 v[0:1], v[34:35], 0, v[0:1]
	v_add_co_u32_e32 v0, vcc, s6, v0
	v_lshrrev_b32_e32 v34, 4, v207
	s_nop 0
	v_addc_co_u32_e32 v1, vcc, 0, v1, vcc
	global_load_dwordx4 v[4:7], v[0:1], off offset:1024
	s_nop 0
	global_load_dwordx4 v[0:3], v[0:1], off offset:1536
	s_waitcnt vmcnt(7)
	v_lshlrev_b32_e32 v46, 16, v20
	v_and_b32_e32 v47, 0xffff0000, v20
	v_cvt_f32_i32_e32 v20, v31
	v_mul_f32_e32 v35, 0xbfb8aa3b, v17
	v_bfe_u32 v17, v206, 2, 2
	v_lshl_or_b32 v76, v34, 3, v17
	v_sub_u32_e32 v17, 0x7f, v31
	v_cvt_f32_i32_e32 v17, v17
	v_lshlrev_b32_e32 v42, 16, v18
	v_and_b32_e32 v43, 0xffff0000, v18
	v_mul_f32_e32 v32, 0xbfb8aa3b, v32
	v_mul_f32_e32 v16, v35, v17
	v_exp_f32_e32 v103, v16
	v_lshlrev_b32_e32 v44, 16, v19
	v_and_b32_e32 v45, 0xffff0000, v19
	v_mul_f32_e32 v20, v32, v20
	v_mul_f32_e32 v16, v103, v42
	v_mul_f32_e32 v17, v103, v43
	v_cvt_pk_bf16_f32 v16, v16, v17
	v_mul_f32_e32 v17, v103, v44
	v_mul_f32_e32 v18, v103, v45
	v_cvt_pk_bf16_f32 v17, v17, v18
	v_mul_f32_e32 v18, v103, v46
	v_mul_f32_e32 v19, v103, v47
	v_lshlrev_b32_e32 v48, 16, v21
	v_and_b32_e32 v49, 0xffff0000, v21
	v_exp_f32_e32 v104, v20
	v_cvt_pk_bf16_f32 v18, v18, v19
	v_mul_f32_e32 v19, v103, v48
	v_mul_f32_e32 v21, v103, v49
	s_movk_i32 s9, 0x50
	v_cvt_pk_bf16_f32 v19, v19, v21
	v_mad_u64_u32 v[20:21], s[6:7], v31, s9, v[30:31]
	v_lshl_add_u32 v105, v20, 1, 0
	s_barrier
	ds_write_b128 v105, v[16:19]
	v_mul_f32_e32 v16, v104, v42
	v_mul_f32_e32 v17, v104, v43
	v_cvt_pk_bf16_f32 v16, v16, v17
	v_mul_f32_e32 v17, v104, v44
	v_mul_f32_e32 v18, v104, v45
	v_cvt_pk_bf16_f32 v17, v17, v18
	v_mul_f32_e32 v18, v104, v46
	v_mul_f32_e32 v19, v104, v47
	v_cvt_pk_bf16_f32 v18, v18, v19
	v_sub_u32_e32 v19, 0x7f, v37
	v_cvt_f32_i32_e32 v20, v19
	v_mul_f32_e32 v19, v104, v48
	v_mul_f32_e32 v21, v104, v49
	v_cvt_pk_bf16_f32 v19, v19, v21
	v_mul_f32_e32 v20, v35, v20
	v_exp_f32_e32 v35, v20
	v_cvt_f32_i32_e32 v20, v37
	ds_write_b128 v105, v[16:19] offset:20480
	s_waitcnt vmcnt(6)
	ds_write_b128 v105, v[22:25] offset:40960
	v_mad_u32_u24 v62, v76, s9, v62
	v_mad_u32_u24 v87, v76, s9, v80
	v_mul_f32_e32 v20, v32, v20
	v_exp_f32_e32 v32, v20
	s_waitcnt vmcnt(5)
	v_lshlrev_b32_e32 v22, 16, v26
	v_and_b32_e32 v23, 0xffff0000, v26
	v_mul_f32_e32 v16, v35, v22
	v_mul_f32_e32 v17, v35, v23
	v_lshlrev_b32_e32 v24, 16, v27
	v_and_b32_e32 v25, 0xffff0000, v27
	v_cvt_pk_bf16_f32 v16, v16, v17
	v_mul_f32_e32 v17, v35, v24
	v_mul_f32_e32 v18, v35, v25
	v_lshlrev_b32_e32 v26, 16, v28
	v_and_b32_e32 v27, 0xffff0000, v28
	v_cvt_pk_bf16_f32 v17, v17, v18
	v_mul_f32_e32 v18, v35, v26
	v_mul_f32_e32 v19, v35, v27
	v_lshlrev_b32_e32 v28, 16, v29
	v_and_b32_e32 v29, 0xffff0000, v29
	v_cvt_pk_bf16_f32 v18, v18, v19
	v_mul_f32_e32 v19, v35, v28
	v_mul_f32_e32 v21, v35, v29
	v_cvt_pk_bf16_f32 v19, v19, v21
	v_mad_u64_u32 v[20:21], s[6:7], v37, s9, v[30:31]
	v_lshl_add_u32 v37, v20, 1, 0
	ds_write_b128 v37, v[16:19]
	v_mul_f32_e32 v16, v32, v22
	v_mul_f32_e32 v17, v32, v23
	v_cvt_pk_bf16_f32 v16, v16, v17
	v_mul_f32_e32 v17, v32, v24
	v_mul_f32_e32 v18, v32, v25
	v_cvt_pk_bf16_f32 v17, v17, v18
	v_mul_f32_e32 v18, v32, v26
	v_mul_f32_e32 v19, v32, v27
	v_cvt_pk_bf16_f32 v18, v18, v19
	v_mul_f32_e32 v19, v32, v28
	v_mul_f32_e32 v20, v32, v29
	v_cvt_pk_bf16_f32 v19, v19, v20
	v_readlane_b32 s6, v254, 42
	v_mov_b32_e32 v30, 0xa00
	ds_write_b128 v37, v[16:19] offset:20480
	s_waitcnt vmcnt(4)
	ds_write_b128 v37, v[38:41] offset:40960
	v_or_b32_e32 v77, s6, v86
	v_mul_u32_u24_e32 v16, 0x50, v76
	v_mad_u32_u24 v46, v76, s9, v30
	v_mad_u32_u24 v17, v76, s9, v77
	v_or_b32_e32 v16, v16, v86
	v_add_u32_e32 v30, v46, v77
	v_or_b32_e32 v46, v46, v86
	v_add_u32_e32 v63, v62, v77
	v_or_b32_e32 v62, v62, v86
	v_or_b32_e32 v86, v87, v86
	v_lshl_add_u32 v106, v17, 1, 0
	v_lshl_add_u32 v107, v16, 1, s72
	v_lshl_add_u32 v109, v46, 1, s72
	v_lshl_add_u32 v110, v63, 1, 0
	v_lshl_add_u32 v111, v62, 1, s72
	v_add_u32_e32 v76, v87, v77
	v_lshl_add_u32 v113, v86, 1, s72
	s_waitcnt lgkmcnt(0)
	s_barrier
	ds_read_b64_tr_b16 v[16:17], v106 offset:40960
	ds_read_b64_tr_b16 v[18:19], v106 offset:41600
	ds_read_b64_tr_b16 v[20:21], v107
	ds_read_b64_tr_b16 v[24:25], v107 offset:32
	ds_read_b64_tr_b16 v[22:23], v107 offset:640
	ds_read_b64_tr_b16 v[26:27], v107 offset:672
	ds_read_b64_tr_b16 v[28:29], v107 offset:64
	ds_read_b64_tr_b16 v[38:39], v107 offset:96
	v_lshl_add_u32 v108, v30, 1, 0
	ds_read_b64_tr_b16 v[30:31], v107 offset:704
	ds_read_b64_tr_b16 v[40:41], v107 offset:736
	ds_read_b64_tr_b16 v[42:43], v108 offset:40960
	ds_read_b64_tr_b16 v[44:45], v108 offset:41600
	ds_read_b64_tr_b16 v[46:47], v109
	ds_read_b64_tr_b16 v[50:51], v109 offset:32
	ds_read_b64_tr_b16 v[54:55], v109 offset:64
	ds_read_b64_tr_b16 v[58:59], v109 offset:96
	ds_read_b64_tr_b16 v[48:49], v109 offset:640
	ds_read_b64_tr_b16 v[52:53], v109 offset:672
	ds_read_b64_tr_b16 v[56:57], v109 offset:704
	ds_read_b64_tr_b16 v[60:61], v109 offset:736
	ds_read_b64_tr_b16 v[62:63], v110 offset:40960
	ds_read_b64_tr_b16 v[64:65], v110 offset:41600
	ds_read_b64_tr_b16 v[66:67], v111
	ds_read_b64_tr_b16 v[70:71], v111 offset:32
	ds_read_b64_tr_b16 v[68:69], v111 offset:640
	ds_read_b64_tr_b16 v[72:73], v111 offset:672
	ds_read_b64_tr_b16 v[74:75], v111 offset:64
	ds_read_b64_tr_b16 v[78:79], v111 offset:96
	v_lshl_add_u32 v112, v76, 1, 0
	ds_read_b64_tr_b16 v[76:77], v111 offset:704
	ds_read_b64_tr_b16 v[80:81], v111 offset:736
	ds_read_b64_tr_b16 v[82:83], v112 offset:40960
	ds_read_b64_tr_b16 v[84:85], v112 offset:41600
	ds_read_b64_tr_b16 v[86:87], v113
	ds_read_b64_tr_b16 v[90:91], v113 offset:32
	ds_read_b64_tr_b16 v[94:95], v113 offset:64
	ds_read_b64_tr_b16 v[98:99], v113 offset:96
	ds_read_b64_tr_b16 v[88:89], v113 offset:640
	ds_read_b64_tr_b16 v[92:93], v113 offset:672
	ds_read_b64_tr_b16 v[96:97], v113 offset:704
	ds_read_b64_tr_b16 v[100:101], v113 offset:736
	v_lshlrev_b32_e32 v34, 10, v34
	s_waitcnt lgkmcnt(14)
	v_mfma_f32_16x16x32_bf16 v[20:23], v[16:19], v[20:23], 0
	v_readlane_b32 s6, v254, 40
	s_lshl_b32 s0, s0, 13
	v_readlane_b32 s7, v254, 55
	v_mfma_f32_16x16x32_bf16 v[24:27], v[16:19], v[24:27], 0
	v_add3_u32 v34, s6, v34, v102
	v_add_u32_e32 v34, 0xf000, v34
	s_add_i32 s0, s0, s7
	v_mfma_f32_16x16x32_bf16 v[28:31], v[16:19], v[28:31], 0
	v_readlane_b32 s20, v254, 19
	v_readlane_b32 s21, v254, 20
	v_readlane_b32 s22, v254, 21
	v_mfma_f32_16x16x32_bf16 v[16:19], v[16:19], v[38:41], 0
	v_readlane_b32 s23, v254, 22
	v_mfma_f32_16x16x32_bf16 v[20:23], v[42:45], v[46:49], v[20:23]
	v_mfma_f32_16x16x32_bf16 v[24:27], v[42:45], v[50:53], v[24:27]
	v_mfma_f32_16x16x32_bf16 v[28:31], v[42:45], v[54:57], v[28:31]
	v_mfma_f32_16x16x32_bf16 v[16:19], v[42:45], v[58:61], v[16:19]
	v_mfma_f32_16x16x32_bf16 v[20:23], v[62:65], v[66:69], v[20:23]
	v_mfma_f32_16x16x32_bf16 v[24:27], v[62:65], v[70:73], v[24:27]
	s_waitcnt lgkmcnt(11)
	v_mfma_f32_16x16x32_bf16 v[28:31], v[62:65], v[74:77], v[28:31]
	s_waitcnt lgkmcnt(10)
	v_mfma_f32_16x16x32_bf16 v[16:19], v[62:65], v[78:81], v[16:19]
	s_waitcnt lgkmcnt(3)
	v_mfma_f32_16x16x32_bf16 v[20:23], v[82:85], v[86:89], v[20:23]
	v_lshl_add_u32 v87, v207, 4, s6
	v_lshlrev_b32_e32 v86, 2, v207
	v_or_b32_e32 v38, s0, v86
	s_waitcnt lgkmcnt(2)
	v_mfma_f32_16x16x32_bf16 v[24:27], v[82:85], v[90:93], v[24:27]
	v_lshlrev_b32_e32 v38, 2, v38
	s_waitcnt lgkmcnt(1)
	v_mfma_f32_16x16x32_bf16 v[28:31], v[82:85], v[94:97], v[28:31]
	s_waitcnt lgkmcnt(0)
	v_mfma_f32_16x16x32_bf16 v[16:19], v[82:85], v[98:101], v[16:19]
	s_nop 2
	ds_write2_b32 v34, v20, v24 offset1:16
	ds_write2_b32 v34, v21, v25 offset0:64 offset1:80
	ds_write2_b32 v34, v22, v26 offset0:128 offset1:144
	ds_write2_b32 v34, v23, v27 offset0:192 offset1:208
	s_nop 0
	ds_write2_b32 v34, v28, v16 offset0:32 offset1:48
	ds_write2_b32 v34, v29, v17 offset0:96 offset1:112
	ds_write2_b32 v34, v30, v18 offset0:160 offset1:176
	ds_write2_b32 v34, v31, v19 offset0:224 offset1:240
	s_waitcnt lgkmcnt(0)
	ds_read_b128 v[16:19], v87 offset:61440
	ds_read_b128 v[20:23], v87 offset:62464
	ds_read_b128 v[24:27], v87 offset:63488
	ds_read_b128 v[28:31], v87 offset:64512
	s_waitcnt lgkmcnt(3)
	buffer_store_dwordx4 v[16:19], v38, s[20:23], 0 offen sc1
	s_waitcnt lgkmcnt(2)
	buffer_store_dwordx4 v[20:23], v38, s[20:23], 0 offen offset:1024 sc1
	s_waitcnt lgkmcnt(1)
	buffer_store_dwordx4 v[24:27], v38, s[20:23], 0 offen offset:2048 sc1
	s_waitcnt lgkmcnt(0)
	buffer_store_dwordx4 v[28:31], v38, s[20:23], 0 offen offset:3072 sc1
	s_waitcnt vmcnt(7)
	v_lshlrev_b32_e32 v16, 16, v12
	v_and_b32_e32 v18, 0xffff0000, v12
	v_mul_f32_e32 v17, v103, v16
	v_mul_f32_e32 v12, v103, v18
	v_cvt_pk_bf16_f32 v12, v17, v12
	v_lshlrev_b32_e32 v17, 16, v13
	v_and_b32_e32 v20, 0xffff0000, v13
	v_mul_f32_e32 v19, v103, v17
	v_mul_f32_e32 v13, v103, v20
	v_cvt_pk_bf16_f32 v13, v19, v13
	v_lshlrev_b32_e32 v19, 16, v14
	v_and_b32_e32 v22, 0xffff0000, v14
	v_mul_f32_e32 v21, v103, v19
	v_mul_f32_e32 v14, v103, v22
	v_cvt_pk_bf16_f32 v14, v21, v14
	v_lshlrev_b32_e32 v21, 16, v15
	v_and_b32_e32 v24, 0xffff0000, v15
	v_mul_f32_e32 v23, v103, v21
	v_mul_f32_e32 v15, v103, v24
	v_cvt_pk_bf16_f32 v15, v23, v15
	s_waitcnt lgkmcnt(0)
	s_barrier
	ds_write_b128 v105, v[12:15]
	v_mul_f32_e32 v12, v104, v16
	v_mul_f32_e32 v13, v104, v18
	v_cvt_pk_bf16_f32 v12, v12, v13
	v_mul_f32_e32 v13, v104, v17
	v_mul_f32_e32 v14, v104, v20
	v_cvt_pk_bf16_f32 v13, v13, v14
	v_mul_f32_e32 v14, v104, v19
	v_mul_f32_e32 v15, v104, v22
	v_cvt_pk_bf16_f32 v14, v14, v15
	v_mul_f32_e32 v15, v104, v21
	v_mul_f32_e32 v16, v104, v24
	v_cvt_pk_bf16_f32 v15, v15, v16
	ds_write_b128 v105, v[12:15] offset:20480
	s_waitcnt vmcnt(6)
	ds_write_b128 v105, v[8:11] offset:40960
	s_waitcnt vmcnt(5)
	v_lshlrev_b32_e32 v8, 16, v4
	v_and_b32_e32 v10, 0xffff0000, v4
	v_mul_f32_e32 v9, v35, v8
	v_mul_f32_e32 v4, v35, v10
	v_cvt_pk_bf16_f32 v4, v9, v4
	v_lshlrev_b32_e32 v9, 16, v5
	v_and_b32_e32 v12, 0xffff0000, v5
	v_mul_f32_e32 v11, v35, v9
	v_mul_f32_e32 v5, v35, v12
	v_cvt_pk_bf16_f32 v5, v11, v5
	v_lshlrev_b32_e32 v11, 16, v6
	v_and_b32_e32 v14, 0xffff0000, v6
	v_mul_f32_e32 v13, v35, v11
	v_mul_f32_e32 v6, v35, v14
	v_cvt_pk_bf16_f32 v6, v13, v6
	v_lshlrev_b32_e32 v13, 16, v7
	v_and_b32_e32 v16, 0xffff0000, v7
	v_mul_f32_e32 v15, v35, v13
	v_mul_f32_e32 v7, v35, v16
	v_cvt_pk_bf16_f32 v7, v15, v7
	ds_write_b128 v37, v[4:7]
	v_mul_f32_e32 v4, v32, v8
	v_mul_f32_e32 v5, v32, v10
	v_cvt_pk_bf16_f32 v4, v4, v5
	v_mul_f32_e32 v5, v32, v9
	v_mul_f32_e32 v6, v32, v12
	v_cvt_pk_bf16_f32 v5, v5, v6
	v_mul_f32_e32 v6, v32, v11
	v_mul_f32_e32 v7, v32, v14
	v_cvt_pk_bf16_f32 v6, v6, v7
	v_mul_f32_e32 v7, v32, v13
	v_mul_f32_e32 v8, v32, v16
	v_cvt_pk_bf16_f32 v7, v7, v8
	ds_write_b128 v37, v[4:7] offset:20480
	s_waitcnt vmcnt(4)
	ds_write_b128 v37, v[0:3] offset:40960
	s_waitcnt lgkmcnt(0)
	s_barrier
	ds_read_b64_tr_b16 v[0:1], v106 offset:40960
	ds_read_b64_tr_b16 v[2:3], v106 offset:41600
	ds_read_b64_tr_b16 v[4:5], v107
	ds_read_b64_tr_b16 v[8:9], v107 offset:32
	ds_read_b64_tr_b16 v[6:7], v107 offset:640
	ds_read_b64_tr_b16 v[10:11], v107 offset:672
	ds_read_b64_tr_b16 v[12:13], v107 offset:64
	ds_read_b64_tr_b16 v[16:17], v107 offset:96
	ds_read_b64_tr_b16 v[14:15], v107 offset:704
	ds_read_b64_tr_b16 v[18:19], v107 offset:736
	ds_read_b64_tr_b16 v[20:21], v108 offset:40960
	ds_read_b64_tr_b16 v[22:23], v108 offset:41600
	ds_read_b64_tr_b16 v[24:25], v109
	ds_read_b64_tr_b16 v[28:29], v109 offset:32
	ds_read_b64_tr_b16 v[38:39], v109 offset:64
	ds_read_b64_tr_b16 v[42:43], v109 offset:96
	ds_read_b64_tr_b16 v[26:27], v109 offset:640
	ds_read_b64_tr_b16 v[30:31], v109 offset:672
	ds_read_b64_tr_b16 v[40:41], v109 offset:704
	ds_read_b64_tr_b16 v[44:45], v109 offset:736
	ds_read_b64_tr_b16 v[46:47], v110 offset:40960
	ds_read_b64_tr_b16 v[48:49], v110 offset:41600
	ds_read_b64_tr_b16 v[50:51], v111
	ds_read_b64_tr_b16 v[54:55], v111 offset:32
	ds_read_b64_tr_b16 v[52:53], v111 offset:640
	ds_read_b64_tr_b16 v[56:57], v111 offset:672
	ds_read_b64_tr_b16 v[58:59], v111 offset:64
	ds_read_b64_tr_b16 v[62:63], v111 offset:96
	ds_read_b64_tr_b16 v[60:61], v111 offset:704
	ds_read_b64_tr_b16 v[64:65], v111 offset:736
	ds_read_b64_tr_b16 v[66:67], v112 offset:40960
	ds_read_b64_tr_b16 v[68:69], v112 offset:41600
	ds_read_b64_tr_b16 v[70:71], v113
	ds_read_b64_tr_b16 v[74:75], v113 offset:32
	ds_read_b64_tr_b16 v[78:79], v113 offset:64
	ds_read_b64_tr_b16 v[82:83], v113 offset:96
	ds_read_b64_tr_b16 v[72:73], v113 offset:640
	ds_read_b64_tr_b16 v[76:77], v113 offset:672
	ds_read_b64_tr_b16 v[80:81], v113 offset:704
	ds_read_b64_tr_b16 v[84:85], v113 offset:736
	s_waitcnt lgkmcnt(14)
	v_mfma_f32_16x16x32_bf16 v[4:7], v[0:3], v[4:7], 0
	s_lshl_b32 s0, s8, 13
	s_add_i32 s0, s0, s7
	s_lshl_b32 s6, s5, 8
	v_mfma_f32_16x16x32_bf16 v[8:11], v[0:3], v[8:11], 0
	s_ashr_i32 s7, s6, 31
	s_lshl_b64 s[6:7], s[6:7], 2
	v_mfma_f32_16x16x32_bf16 v[12:15], v[0:3], v[12:15], 0
	v_mfma_f32_16x16x32_bf16 v[0:3], v[0:3], v[16:19], 0
	v_or_b32_e32 v16, s0, v86
	v_lshlrev_b32_e32 v16, 2, v16
	s_add_u32 s0, s48, s6
	v_mfma_f32_16x16x32_bf16 v[4:7], v[20:23], v[24:27], v[4:7]
	s_addc_u32 s6, s49, s7
	s_add_u32 s76, s0, 0x53c0
	s_addc_u32 s77, s6, 0
	v_mfma_f32_16x16x32_bf16 v[8:11], v[20:23], v[28:31], v[8:11]
	v_mfma_f32_16x16x32_bf16 v[12:15], v[20:23], v[38:41], v[12:15]
	v_mfma_f32_16x16x32_bf16 v[0:3], v[20:23], v[42:45], v[0:3]
	v_mfma_f32_16x16x32_bf16 v[4:7], v[46:49], v[50:53], v[4:7]
	v_mfma_f32_16x16x32_bf16 v[8:11], v[46:49], v[54:57], v[8:11]
	s_waitcnt lgkmcnt(11)
	v_mfma_f32_16x16x32_bf16 v[12:15], v[46:49], v[58:61], v[12:15]
	s_waitcnt lgkmcnt(10)
	v_mfma_f32_16x16x32_bf16 v[0:3], v[46:49], v[62:65], v[0:3]
	s_waitcnt lgkmcnt(3)
	v_mfma_f32_16x16x32_bf16 v[4:7], v[66:69], v[70:73], v[4:7]
	s_waitcnt lgkmcnt(2)
	v_mfma_f32_16x16x32_bf16 v[8:11], v[66:69], v[74:77], v[8:11]
	s_waitcnt lgkmcnt(1)
	v_mfma_f32_16x16x32_bf16 v[12:15], v[66:69], v[78:81], v[12:15]
	s_waitcnt lgkmcnt(0)
	v_mfma_f32_16x16x32_bf16 v[0:3], v[66:69], v[82:85], v[0:3]
	s_nop 3
	ds_write2_b32 v34, v4, v8 offset1:16
	ds_write2_b32 v34, v5, v9 offset0:64 offset1:80
	ds_write2_b32 v34, v6, v10 offset0:128 offset1:144
	ds_write2_b32 v34, v7, v11 offset0:192 offset1:208
	ds_write2_b32 v34, v12, v0 offset0:32 offset1:48
	ds_write2_b32 v34, v13, v1 offset0:96 offset1:112
	ds_write2_b32 v34, v14, v2 offset0:160 offset1:176
	ds_write2_b32 v34, v15, v3 offset0:224 offset1:240
	s_waitcnt lgkmcnt(0)
	ds_read_b128 v[0:3], v87 offset:61440
	ds_read_b128 v[4:7], v87 offset:62464
	ds_read_b128 v[8:11], v87 offset:63488
	ds_read_b128 v[12:15], v87 offset:64512
	s_waitcnt lgkmcnt(3)
	buffer_store_dwordx4 v[0:3], v16, s[20:23], 0 offen sc1
	s_waitcnt lgkmcnt(2)
	buffer_store_dwordx4 v[4:7], v16, s[20:23], 0 offen offset:1024 sc1
	s_waitcnt lgkmcnt(1)
	buffer_store_dwordx4 v[8:11], v16, s[20:23], 0 offen offset:2048 sc1
	s_waitcnt lgkmcnt(0)
	buffer_store_dwordx4 v[12:15], v16, s[20:23], 0 offen offset:3072 sc1
	s_waitcnt lgkmcnt(0)

.LBB0_653:
	s_mul_hi_u32 s0, s12, 0xaaaaaaab
	s_lshr_b32 s13, s0, 1
	s_mul_i32 s16, s13, -3
	s_add_i32 s16, s16, s12
	s_cmp_lt_i32 s16, 2
	s_mov_b64 s[6:7], -1
	s_cbranch_scc1 .LBB0_656
	s_mov_b64 s[6:7], 0
	s_mov_b64 s[10:11], -1
	s_cmp_eq_u32 s16, 2
	s_mov_b32 s95, s13
	s_mov_b64 s[76:77], 0
	s_mov_b32 s94, s18
	s_cbranch_scc0 .LBB0_656
	s_lshl_b32 s8, s13, 1
	s_mul_hi_u32 s0, s8, 0x78787879
	s_lshr_b32 s0, s0, 4
	s_mul_i32 s0, s0, 34
	s_sub_i32 s0, s8, s0
	s_mul_hi_u32 s9, s12, 0xa0a0a0a1
	s_lshr_b32 s10, s9, 5
	s_lshr_b32 s19, s9, 7
	s_bfe_u32 s11, s9, 0x20005
	s_lshl_b32 s9, s0, 7
	s_cmp_eq_u32 s0, 0
	s_movk_i32 s21, 0xff00
	s_cselect_b32 s17, 8, 12
	s_cselect_b32 s20, 0x4000, s21
	s_or_b32 s8, s8, 1
	s_add_i32 s20, s20, s9
	s_mul_hi_u32 s9, s8, 0x78787879
	s_lshr_b32 s9, s9, 4
	s_lshl_b32 s17, s19, s17
	s_mul_i32 s9, s9, 34
	s_add_i32 s20, s20, s17
	s_sub_i32 s17, s8, s9
	s_lshl_b32 s8, s17, 7
	s_cmp_eq_u32 s17, 1
	s_cselect_b32 s9, 8, 12
	s_cselect_b32 s21, 0x4000, s21
	s_lshl_b32 s9, s19, s9
	s_add_i32 s19, s21, s8
	s_lshl_b32 s8, s5, 3
	s_or_b32 s8, s8, s11
	s_add_i32 s19, s19, s9
	s_ashr_i32 s9, s8, 31
	s_lshl_b64 s[8:9], s[8:9], 2
	s_add_u32 s8, s42, s8
	s_addc_u32 s9, s43, s9
	global_load_dword v0, v33, s[8:9]
	global_load_dword v1, v33, s[8:9] offset:16
	s_mov_b32 s8, 0xbfb8aa3b
	s_mov_b32 s9, 0x3f317218
	s_mov_b32 s21, 0x7f800000
	s_mov_b32 s22, 0x33800000
	v_ashrrev_i32_e32 v31, 3, v206
	v_and_b32_e32 v16, 15, v206
	v_lshlrev_b32_e32 v102, 2, v16
	v_and_b32_e32 v86, 12, v102
	v_mov_b32_e32 v62, 0x1400
	v_mov_b32_e32 v80, 0x1e00
	s_mov_b32 s94, 2
	s_waitcnt vmcnt(1)
	v_mul_f32_e32 v2, 0xbfb8aa3b, v0
	s_waitcnt vmcnt(0)
	v_mul_f32_e32 v3, 0xbfb8aa3b, v1
	v_fma_f32 v4, v0, s8, -v2
	v_rndne_f32_e32 v5, v2
	v_fma_f32 v6, v1, s8, -v3
	v_rndne_f32_e32 v7, v3
	v_fmac_f32_e32 v4, 0xb2a5705f, v0
	v_sub_f32_e32 v2, v2, v5
	v_fmac_f32_e32 v6, 0xb2a5705f, v1
	v_sub_f32_e32 v3, v3, v7
	v_add_f32_e32 v2, v2, v4
	v_cvt_i32_f32_e32 v5, v5
	v_add_f32_e32 v3, v3, v6
	v_exp_f32_e32 v2, v2
	v_cvt_i32_f32_e32 v7, v7
	v_exp_f32_e32 v3, v3
	s_mov_b32 s8, 0x42ce8ed0
	v_ldexp_f32 v2, v2, v5
	v_cmp_nlt_f32_e32 vcc, s8, v0
	v_ldexp_f32 v3, v3, v7
	s_nop 0
	v_cndmask_b32_e32 v2, 0, v2, vcc
	v_cmp_nlt_f32_e32 vcc, s8, v1
	s_mov_b32 s8, 0xc2b17218
	s_nop 0
	v_cndmask_b32_e32 v3, 0, v3, vcc
	v_cmp_ngt_f32_e32 vcc, s8, v0
	s_nop 1
	v_cndmask_b32_e32 v17, v227, v2, vcc
	v_cmp_ngt_f32_e32 vcc, s8, v1
	v_add_f32_e32 v1, 1.0, v17
	v_add_f32_e32 v4, -1.0, v1
	v_cndmask_b32_e32 v0, v227, v3, vcc
	v_add_f32_e32 v20, 1.0, v0
	v_frexp_mant_f32_e32 v5, v1
	v_cvt_f64_f32_e32 v[2:3], v1
	s_mov_b32 s8, 0x3f2aaaab
	v_add_f32_e32 v21, -1.0, v20
	v_sub_f32_e32 v6, v4, v1
	v_frexp_exp_i32_f64_e32 v2, v[2:3]
	v_cmp_gt_f32_e32 vcc, s8, v5
	v_sub_f32_e32 v4, v17, v4
	v_sub_f32_e32 v3, v21, v20
	v_add_f32_e32 v6, 1.0, v6
	v_subbrev_co_u32_e32 v2, vcc, 0, v2, vcc
	v_add_f32_e32 v22, 1.0, v3
	v_add_f32_e32 v3, v4, v6
	v_sub_u32_e32 v4, 0, v2
	v_ldexp_f32 v1, v1, v4
	v_ldexp_f32 v3, v3, v4
	v_add_f32_e32 v4, -1.0, v1
	v_add_f32_e32 v6, 1.0, v1
	v_add_f32_e32 v5, 1.0, v4
	v_add_f32_e32 v7, -1.0, v6
	v_sub_f32_e32 v5, v1, v5
	v_sub_f32_e32 v1, v1, v7
	v_add_f32_e32 v1, v3, v1
	v_add_f32_e32 v7, v3, v5
	v_add_f32_e32 v3, v6, v1
	v_rcp_f32_e32 v10, v3
	v_add_f32_e32 v5, v4, v7
	v_sub_f32_e32 v6, v6, v3
	v_add_f32_e32 v1, v1, v6
	v_mul_f32_e32 v12, v5, v10
	v_mul_f32_e32 v6, v3, v12
	v_fma_f32 v8, v12, v3, -v6
	v_sub_f32_e32 v4, v4, v5
	v_fmac_f32_e32 v8, v12, v1
	v_add_f32_e32 v11, v7, v4
	v_add_f32_e32 v4, v6, v8
	v_sub_f32_e32 v7, v5, v4
	v_mov_b32_e32 v9, v4
	v_pk_add_f32 v[4:5], v[4:5], v[6:7] neg_lo:[0,1] neg_hi:[0,1]
	v_cvt_f32_i32_e32 v2, v2
	v_pk_add_f32 v[4:5], v[4:5], v[8:9] neg_lo:[0,1] neg_hi:[0,1]
	v_cmp_neq_f32_e32 vcc, s21, v17
	v_add_f32_e32 v5, v11, v5
	v_add_f32_e32 v4, v4, v5
	v_add_f32_e32 v5, v7, v4
	v_mul_f32_e32 v9, v10, v5
	v_mul_f32_e32 v6, v3, v9
	v_fma_f32 v8, v9, v3, -v6
	v_sub_f32_e32 v7, v7, v5
	v_fmac_f32_e32 v8, v9, v1
	v_add_f32_e32 v11, v4, v7
	v_add_f32_e32 v13, v12, v9
	v_add_f32_e32 v4, v6, v8
	v_sub_f32_e32 v3, v13, v12
	v_sub_f32_e32 v7, v5, v4
	v_sub_f32_e32 v1, v9, v3
	v_mov_b32_e32 v9, v4
	v_pk_add_f32 v[4:5], v[4:5], v[6:7] neg_lo:[0,1] neg_hi:[0,1]
	s_nop 0
	v_pk_add_f32 v[4:5], v[4:5], v[8:9] neg_lo:[0,1] neg_hi:[0,1]
	s_nop 0
	v_add_f32_e32 v3, v11, v5
	v_add_f32_e32 v3, v4, v3
	v_add_f32_e32 v3, v7, v3
	v_mul_f32_e32 v3, v10, v3
	v_add_f32_e32 v1, v1, v3
	v_add_f32_e32 v3, v13, v1
	v_mul_f32_e32 v4, v3, v3
	v_fmamk_f32 v7, v4, 0x3e9b6dac, v252
	v_sub_f32_e32 v6, v3, v13
	v_ldexp_f32 v5, v3, 1
	v_mul_f32_e32 v3, v3, v4
	v_fmaak_f32 v201, v4, v7, 0x3f2aaada
	v_sub_f32_e32 v1, v1, v6
	v_pk_mul_f32 v[6:7], v[2:3], v[200:201]
	v_ldexp_f32 v1, v1, 1
	v_fma_f32 v4, v2, s9, -v6
	v_fmac_f32_e32 v4, 0xb102e308, v2
	v_pk_add_f32 v[2:3], v[6:7], v[4:5]
	v_mov_b32_e32 v8, v6
	v_sub_f32_e32 v9, v3, v5
	v_pk_add_f32 v[10:11], v[2:3], v[6:7] neg_lo:[0,1] neg_hi:[0,1]
	v_sub_f32_e32 v7, v7, v9
	v_add_f32_e32 v9, v1, v7
	v_pk_add_f32 v[14:15], v[2:3], v[8:9]
	v_mov_b32_e32 v5, v2
	v_mov_b32_e32 v11, v15
	v_pk_add_f32 v[18:19], v[4:5], v[10:11] neg_lo:[0,1] neg_hi:[0,1]
	v_pk_add_f32 v[4:5], v[4:5], v[10:11]
	v_mov_b32_e32 v6, v3
	v_mov_b32_e32 v13, v2
	v_pk_add_f32 v[2:3], v[4:5], v[2:3] op_sel:[1,0] op_sel_hi:[0,1] neg_lo:[0,1] neg_hi:[0,1]
	v_mov_b32_e32 v12, v9
	v_mov_b32_e32 v8, v15
	v_mov_b32_e32 v9, v5
	v_mov_b32_e32 v7, v2
	v_pk_add_f32 v[10:11], v[14:15], v[2:3] op_sel_hi:[1,0] neg_lo:[0,1] neg_hi:[0,1]
	v_pk_add_f32 v[2:3], v[8:9], v[6:7] neg_lo:[0,1] neg_hi:[0,1]
	v_mov_b32_e32 v10, v18
	v_pk_add_f32 v[2:3], v[12:13], v[2:3] neg_lo:[0,1] neg_hi:[0,1]
	v_mov_b32_e32 v19, v5
	v_pk_add_f32 v[6:7], v[10:11], v[2:3]
	s_nop 0
	v_pk_add_f32 v[8:9], v[6:7], v[6:7] op_sel:[0,1] op_sel_hi:[1,0]
	s_nop 0
	v_pk_add_f32 v[4:5], v[4:5], v[8:9] op_sel:[1,0] op_sel_hi:[0,1]
	v_mov_b32_e32 v7, v4
	v_mov_b32_e32 v3, v8
	v_pk_add_f32 v[8:9], v[6:7], v[18:19] neg_lo:[0,1] neg_hi:[0,1]
	s_nop 0
	v_sub_f32_e32 v1, v6, v8
	v_pk_add_f32 v[2:3], v[2:3], v[8:9] neg_lo:[0,1] neg_hi:[0,1]
	v_sub_f32_e32 v1, v18, v1
	v_add_f32_e32 v1, v2, v1
	v_add_f32_e32 v1, v1, v3
	v_add_f32_e32 v1, v4, v1
	v_cndmask_b32_e32 v1, v227, v1, vcc
	v_cmp_lt_f32_e64 vcc, |v17|, s22
	v_frexp_mant_f32_e32 v4, v20
	v_cvt_f64_f32_e32 v[2:3], v20
	v_cndmask_b32_e32 v17, v1, v17, vcc
	v_frexp_exp_i32_f64_e32 v2, v[2:3]
	v_cmp_gt_f32_e32 vcc, s8, v4
	v_sub_f32_e32 v1, v0, v21
	v_add_f32_e32 v1, v1, v22
	v_subbrev_co_u32_e32 v10, vcc, 0, v2, vcc
	v_sub_u32_e32 v2, 0, v10
	v_ldexp_f32 v3, v20, v2
	v_ldexp_f32 v1, v1, v2
	v_add_f32_e32 v2, -1.0, v3
	v_add_f32_e32 v5, 1.0, v3
	v_add_f32_e32 v4, 1.0, v2
	v_add_f32_e32 v6, -1.0, v5
	v_sub_f32_e32 v4, v3, v4
	v_sub_f32_e32 v3, v3, v6
	v_add_f32_e32 v4, v1, v4
	v_add_f32_e32 v1, v1, v3
	v_add_f32_e32 v11, v5, v1
	v_rcp_f32_e32 v12, v11
	v_sub_f32_e32 v3, v5, v11
	v_add_f32_e32 v1, v1, v3
	v_add_f32_e32 v3, v2, v4
	v_sub_f32_e32 v2, v2, v3
	v_mul_f32_e32 v14, v3, v12
	v_add_f32_e32 v13, v4, v2
	v_mul_f32_e32 v4, v11, v14
	v_fma_f32 v6, v14, v11, -v4
	v_fmac_f32_e32 v6, v14, v1
	v_add_f32_e32 v2, v4, v6
	v_sub_f32_e32 v5, v3, v2
	v_pk_add_f32 v[8:9], v[2:3], v[4:5] neg_lo:[0,1] neg_hi:[0,1]
	v_mov_b32_e32 v7, v2
	v_pk_add_f32 v[2:3], v[8:9], v[6:7] neg_lo:[0,1] neg_hi:[0,1]
	s_lshl_b32 s8, s11, 7
	v_add_f32_e32 v3, v13, v3
	v_add_f32_e32 v2, v2, v3
	v_add_f32_e32 v3, v5, v2
	v_mul_f32_e32 v13, v12, v3
	v_mul_f32_e32 v4, v11, v13
	v_fma_f32 v6, v13, v11, -v4
	v_fmac_f32_e32 v6, v13, v1
	v_sub_f32_e32 v1, v5, v3
	v_add_f32_e32 v1, v2, v1
	v_add_f32_e32 v2, v4, v6
	v_sub_f32_e32 v5, v3, v2
	v_pk_add_f32 v[8:9], v[2:3], v[4:5] neg_lo:[0,1] neg_hi:[0,1]
	v_mov_b32_e32 v7, v2
	v_pk_add_f32 v[2:3], v[8:9], v[6:7] neg_lo:[0,1] neg_hi:[0,1]
	s_add_u32 s8, s70, s8
	v_add_f32_e32 v1, v1, v3
	v_add_f32_e32 v1, v2, v1
	v_add_f32_e32 v3, v14, v13
	v_add_f32_e32 v1, v5, v1
	v_sub_f32_e32 v2, v3, v14
	v_mul_f32_e32 v1, v12, v1
	v_sub_f32_e32 v2, v13, v2
	v_add_f32_e32 v1, v2, v1
	v_add_f32_e32 v4, v3, v1
	v_mul_f32_e32 v6, v4, v4
	v_fmamk_f32 v2, v6, 0x3e9b6dac, v252
	v_fmaak_f32 v201, v6, v2, 0x3f2aaada
	v_cvt_f32_i32_e32 v2, v10
	v_sub_f32_e32 v3, v4, v3
	v_sub_f32_e32 v1, v1, v3
	v_mul_f32_e32 v3, v4, v6
	v_pk_mul_f32 v[6:7], v[2:3], v[200:201]
	v_ldexp_f32 v5, v4, 1
	v_fma_f32 v4, v2, s9, -v6
	v_fmac_f32_e32 v4, 0xb102e308, v2
	v_pk_add_f32 v[2:3], v[6:7], v[4:5]
	v_ldexp_f32 v1, v1, 1
	v_sub_f32_e32 v5, v3, v5
	v_sub_f32_e32 v5, v7, v5
	v_add_f32_e32 v9, v1, v5
	v_lshlrev_b32_e32 v1, 3, v206
	v_and_b32_e32 v30, 56, v1
	v_add_u32_e32 v12, s20, v31
	v_mov_b32_e32 v8, v6
	s_addc_u32 s9, s71, 0
	v_lshlrev_b32_e32 v32, 1, v30
	v_ashrrev_i32_e32 v13, 31, v12
	v_pk_add_f32 v[6:7], v[2:3], v[6:7] neg_lo:[0,1] neg_hi:[0,1]
	v_pk_add_f32 v[10:11], v[2:3], v[8:9]
	v_lshl_add_u64 v[34:35], s[8:9], 0, v[32:33]
	v_lshlrev_b64 v[12:13], 13, v[12:13]
	v_lshl_add_u64 v[12:13], v[34:35], 0, v[12:13]
	s_movk_i32 s8, 0x1000
	v_mov_b32_e32 v7, v11
	v_mov_b32_e32 v5, v2
	v_add_co_u32_e32 v12, vcc, s8, v12
	v_pk_add_f32 v[14:15], v[4:5], v[6:7] neg_lo:[0,1] neg_hi:[0,1]
	v_pk_add_f32 v[4:5], v[4:5], v[6:7]
	v_addc_co_u32_e32 v13, vcc, 0, v13, vcc
	v_pk_add_f32 v[6:7], v[4:5], v[2:3] op_sel:[1,0] op_sel_hi:[0,1] neg_lo:[0,1] neg_hi:[0,1]
	global_load_dwordx4 v[18:21], v[12:13], off offset:1024
	v_pk_add_f32 v[22:23], v[10:11], v[6:7] op_sel_hi:[1,0] neg_lo:[0,1] neg_hi:[0,1]
	v_mov_b32_e32 v10, v11
	v_mov_b32_e32 v11, v5
	v_mov_b32_e32 v24, v3
	v_mov_b32_e32 v25, v6
	v_pk_add_f32 v[6:7], v[10:11], v[24:25] neg_lo:[0,1] neg_hi:[0,1]
	v_mov_b32_e32 v8, v9
	v_mov_b32_e32 v9, v2
	v_pk_add_f32 v[2:3], v[8:9], v[6:7] neg_lo:[0,1] neg_hi:[0,1]
	v_mov_b32_e32 v22, v14
	v_pk_add_f32 v[6:7], v[22:23], v[2:3]
	v_mov_b32_e32 v15, v5
	v_pk_add_f32 v[8:9], v[6:7], v[6:7] op_sel:[0,1] op_sel_hi:[1,0]
	v_cmp_neq_f32_e32 vcc, s21, v0
	v_pk_add_f32 v[4:5], v[4:5], v[8:9] op_sel:[1,0] op_sel_hi:[0,1]
	v_mov_b32_e32 v7, v4
	v_pk_add_f32 v[10:11], v[6:7], v[14:15] neg_lo:[0,1] neg_hi:[0,1]
	v_mov_b32_e32 v3, v8
	v_sub_f32_e32 v1, v6, v10
	v_pk_add_f32 v[2:3], v[2:3], v[10:11] neg_lo:[0,1] neg_hi:[0,1]
	v_sub_f32_e32 v1, v14, v1
	v_add_f32_e32 v1, v2, v1
	v_add_f32_e32 v1, v1, v3
	v_add_f32_e32 v1, v4, v1
	v_cndmask_b32_e32 v1, v227, v1, vcc
	v_cmp_lt_f32_e64 vcc, |v0|, s22
	global_load_dwordx4 v[22:25], v[12:13], off offset:1536
	v_cndmask_b32_e32 v32, v1, v0, vcc
	v_add_u32_e32 v0, 0x200, v206
	v_ashrrev_i32_e32 v37, 3, v0
	v_add_u32_e32 v0, s20, v37
	v_ashrrev_i32_e32 v1, 31, v0
	v_lshlrev_b64 v[0:1], 13, v[0:1]
	v_lshl_add_u64 v[0:1], v[34:35], 0, v[0:1]
	v_add_co_u32_e32 v0, vcc, s8, v0
	s_nop 0
	v_addc_co_u32_e32 v1, vcc, 0, v1, vcc
	global_load_dwordx4 v[26:29], v[0:1], off offset:1024
	global_load_dwordx4 v[38:41], v[0:1], off offset:1536
	v_add_u32_e32 v0, s19, v31
	v_ashrrev_i32_e32 v1, 31, v0
	v_lshlrev_b64 v[0:1], 13, v[0:1]
	v_lshl_add_u64 v[0:1], v[34:35], 0, v[0:1]
	v_add_co_u32_e32 v0, vcc, s8, v0
	s_nop 0
	v_addc_co_u32_e32 v1, vcc, 0, v1, vcc
	global_load_dwordx4 v[12:15], v[0:1], off offset:1024
	global_load_dwordx4 v[8:11], v[0:1], off offset:1536
	v_add_u32_e32 v0, s19, v37
	v_ashrrev_i32_e32 v1, 31, v0
	v_lshlrev_b64 v[0:1], 13, v[0:1]
	v_lshl_add_u64 v[0:1], v[34:35], 0, v[0:1]
	v_add_co_u32_e32 v0, vcc, s8, v0
	v_lshrrev_b32_e32 v34, 4, v207
	s_nop 0
	v_addc_co_u32_e32 v1, vcc, 0, v1, vcc
	global_load_dwordx4 v[4:7], v[0:1], off offset:1024
	s_nop 0
	global_load_dwordx4 v[0:3], v[0:1], off offset:1536
	s_waitcnt vmcnt(7)
	v_lshlrev_b32_e32 v46, 16, v20
	v_and_b32_e32 v47, 0xffff0000, v20
	v_cvt_f32_i32_e32 v20, v31
	v_mul_f32_e32 v35, 0xbfb8aa3b, v17
	v_bfe_u32 v17, v206, 2, 2
	v_lshl_or_b32 v76, v34, 3, v17
	v_sub_u32_e32 v17, 0x7f, v31
	v_cvt_f32_i32_e32 v17, v17
	v_lshlrev_b32_e32 v42, 16, v18
	v_and_b32_e32 v43, 0xffff0000, v18
	v_mul_f32_e32 v32, 0xbfb8aa3b, v32
	v_mul_f32_e32 v16, v35, v17
	v_exp_f32_e32 v103, v16
	v_lshlrev_b32_e32 v44, 16, v19
	v_and_b32_e32 v45, 0xffff0000, v19
	v_mul_f32_e32 v20, v32, v20
	v_mul_f32_e32 v16, v103, v42
	v_mul_f32_e32 v17, v103, v43
	v_cvt_pk_bf16_f32 v16, v16, v17
	v_mul_f32_e32 v17, v103, v44
	v_mul_f32_e32 v18, v103, v45
	v_cvt_pk_bf16_f32 v17, v17, v18
	v_mul_f32_e32 v18, v103, v46
	v_mul_f32_e32 v19, v103, v47
	v_lshlrev_b32_e32 v48, 16, v21
	v_and_b32_e32 v49, 0xffff0000, v21
	v_exp_f32_e32 v104, v20
	v_cvt_pk_bf16_f32 v18, v18, v19
	v_mul_f32_e32 v19, v103, v48
	v_mul_f32_e32 v21, v103, v49
	s_movk_i32 s19, 0x50
	v_cvt_pk_bf16_f32 v19, v19, v21
	v_mad_u64_u32 v[20:21], s[8:9], v31, s19, v[30:31]
	v_lshl_add_u32 v105, v20, 1, 0
	s_barrier
	ds_write_b128 v105, v[16:19]
	v_mul_f32_e32 v16, v104, v42
	v_mul_f32_e32 v17, v104, v43
	v_cvt_pk_bf16_f32 v16, v16, v17
	v_mul_f32_e32 v17, v104, v44
	v_mul_f32_e32 v18, v104, v45
	v_cvt_pk_bf16_f32 v17, v17, v18
	v_mul_f32_e32 v18, v104, v46
	v_mul_f32_e32 v19, v104, v47
	v_cvt_pk_bf16_f32 v18, v18, v19
	v_sub_u32_e32 v19, 0x7f, v37
	v_cvt_f32_i32_e32 v20, v19
	v_mul_f32_e32 v19, v104, v48
	v_mul_f32_e32 v21, v104, v49
	v_cvt_pk_bf16_f32 v19, v19, v21
	v_mul_f32_e32 v20, v35, v20
	v_exp_f32_e32 v35, v20
	v_cvt_f32_i32_e32 v20, v37
	ds_write_b128 v105, v[16:19] offset:20480
	s_waitcnt vmcnt(6)
	ds_write_b128 v105, v[22:25] offset:40960
	v_mad_u32_u24 v62, v76, s19, v62
	v_mad_u32_u24 v87, v76, s19, v80
	v_mul_f32_e32 v20, v32, v20
	v_exp_f32_e32 v32, v20
	s_waitcnt vmcnt(5)
	v_lshlrev_b32_e32 v22, 16, v26
	v_and_b32_e32 v23, 0xffff0000, v26
	v_mul_f32_e32 v16, v35, v22
	v_mul_f32_e32 v17, v35, v23
	v_lshlrev_b32_e32 v24, 16, v27
	v_and_b32_e32 v25, 0xffff0000, v27
	v_cvt_pk_bf16_f32 v16, v16, v17
	v_mul_f32_e32 v17, v35, v24
	v_mul_f32_e32 v18, v35, v25
	v_lshlrev_b32_e32 v26, 16, v28
	v_and_b32_e32 v27, 0xffff0000, v28
	v_cvt_pk_bf16_f32 v17, v17, v18
	v_mul_f32_e32 v18, v35, v26
	v_mul_f32_e32 v19, v35, v27
	v_lshlrev_b32_e32 v28, 16, v29
	v_and_b32_e32 v29, 0xffff0000, v29
	v_cvt_pk_bf16_f32 v18, v18, v19
	v_mul_f32_e32 v19, v35, v28
	v_mul_f32_e32 v21, v35, v29
	v_cvt_pk_bf16_f32 v19, v19, v21
	v_mad_u64_u32 v[20:21], s[8:9], v37, s19, v[30:31]
	v_lshl_add_u32 v37, v20, 1, 0
	ds_write_b128 v37, v[16:19]
	v_mul_f32_e32 v16, v32, v22
	v_mul_f32_e32 v17, v32, v23
	v_cvt_pk_bf16_f32 v16, v16, v17
	v_mul_f32_e32 v17, v32, v24
	v_mul_f32_e32 v18, v32, v25
	v_cvt_pk_bf16_f32 v17, v17, v18
	v_mul_f32_e32 v18, v32, v26
	v_mul_f32_e32 v19, v32, v27
	v_cvt_pk_bf16_f32 v18, v18, v19
	v_mul_f32_e32 v19, v32, v28
	v_mul_f32_e32 v20, v32, v29
	v_cvt_pk_bf16_f32 v19, v19, v20
	v_readlane_b32 s8, v254, 42
	v_mov_b32_e32 v30, 0xa00
	ds_write_b128 v37, v[16:19] offset:20480
	s_waitcnt vmcnt(4)
	ds_write_b128 v37, v[38:41] offset:40960
	v_or_b32_e32 v77, s8, v86
	v_mul_u32_u24_e32 v16, 0x50, v76
	v_mad_u32_u24 v46, v76, s19, v30
	v_mad_u32_u24 v17, v76, s19, v77
	v_or_b32_e32 v16, v16, v86
	v_add_u32_e32 v30, v46, v77
	v_or_b32_e32 v46, v46, v86
	v_add_u32_e32 v63, v62, v77
	v_or_b32_e32 v62, v62, v86
	v_or_b32_e32 v86, v87, v86
	v_lshl_add_u32 v106, v17, 1, 0
	v_lshl_add_u32 v107, v16, 1, s72
	v_lshl_add_u32 v109, v46, 1, s72
	v_lshl_add_u32 v110, v63, 1, 0
	v_lshl_add_u32 v111, v62, 1, s72
	v_add_u32_e32 v76, v87, v77
	v_lshl_add_u32 v113, v86, 1, s72
	s_waitcnt lgkmcnt(0)
	s_barrier
	ds_read_b64_tr_b16 v[16:17], v106 offset:40960
	ds_read_b64_tr_b16 v[18:19], v106 offset:41600
	ds_read_b64_tr_b16 v[20:21], v107
	ds_read_b64_tr_b16 v[24:25], v107 offset:32
	ds_read_b64_tr_b16 v[22:23], v107 offset:640
	ds_read_b64_tr_b16 v[26:27], v107 offset:672
	ds_read_b64_tr_b16 v[28:29], v107 offset:64
	ds_read_b64_tr_b16 v[38:39], v107 offset:96
	v_lshl_add_u32 v108, v30, 1, 0
	ds_read_b64_tr_b16 v[30:31], v107 offset:704
	ds_read_b64_tr_b16 v[40:41], v107 offset:736
	ds_read_b64_tr_b16 v[42:43], v108 offset:40960
	ds_read_b64_tr_b16 v[44:45], v108 offset:41600
	ds_read_b64_tr_b16 v[46:47], v109
	ds_read_b64_tr_b16 v[50:51], v109 offset:32
	ds_read_b64_tr_b16 v[54:55], v109 offset:64
	ds_read_b64_tr_b16 v[58:59], v109 offset:96
	ds_read_b64_tr_b16 v[48:49], v109 offset:640
	ds_read_b64_tr_b16 v[52:53], v109 offset:672
	ds_read_b64_tr_b16 v[56:57], v109 offset:704
	ds_read_b64_tr_b16 v[60:61], v109 offset:736
	ds_read_b64_tr_b16 v[62:63], v110 offset:40960
	ds_read_b64_tr_b16 v[64:65], v110 offset:41600
	ds_read_b64_tr_b16 v[66:67], v111
	ds_read_b64_tr_b16 v[70:71], v111 offset:32
	ds_read_b64_tr_b16 v[68:69], v111 offset:640
	ds_read_b64_tr_b16 v[72:73], v111 offset:672
	ds_read_b64_tr_b16 v[74:75], v111 offset:64
	ds_read_b64_tr_b16 v[78:79], v111 offset:96
	v_lshl_add_u32 v112, v76, 1, 0
	ds_read_b64_tr_b16 v[76:77], v111 offset:704
	ds_read_b64_tr_b16 v[80:81], v111 offset:736
	ds_read_b64_tr_b16 v[82:83], v112 offset:40960
	ds_read_b64_tr_b16 v[84:85], v112 offset:41600
	ds_read_b64_tr_b16 v[86:87], v113
	ds_read_b64_tr_b16 v[90:91], v113 offset:32
	ds_read_b64_tr_b16 v[94:95], v113 offset:64
	ds_read_b64_tr_b16 v[98:99], v113 offset:96
	ds_read_b64_tr_b16 v[88:89], v113 offset:640
	ds_read_b64_tr_b16 v[92:93], v113 offset:672
	ds_read_b64_tr_b16 v[96:97], v113 offset:704
	ds_read_b64_tr_b16 v[100:101], v113 offset:736
	s_mul_i32 s8, s10, 34
	v_lshlrev_b32_e32 v34, 10, v34
	s_waitcnt lgkmcnt(14)
	v_mfma_f32_16x16x32_bf16 v[20:23], v[16:19], v[20:23], 0
	v_readlane_b32 s9, v254, 40
	s_add_i32 s0, s0, s8
	s_lshl_b32 s0, s0, 13
	v_mfma_f32_16x16x32_bf16 v[24:27], v[16:19], v[24:27], 0
	v_add3_u32 v34, s9, v34, v102
	v_add_u32_e32 v34, 0xf000, v34
	v_readlane_b32 s19, v254, 54
	v_mfma_f32_16x16x32_bf16 v[28:31], v[16:19], v[28:31], 0
	s_add_i32 s0, s0, s19
	v_readlane_b32 s20, v254, 19
	v_readlane_b32 s21, v254, 20
	v_mfma_f32_16x16x32_bf16 v[16:19], v[16:19], v[38:41], 0
	v_readlane_b32 s22, v254, 21
	v_readlane_b32 s23, v254, 22
	v_mfma_f32_16x16x32_bf16 v[20:23], v[42:45], v[46:49], v[20:23]
	v_mfma_f32_16x16x32_bf16 v[24:27], v[42:45], v[50:53], v[24:27]
	v_mfma_f32_16x16x32_bf16 v[28:31], v[42:45], v[54:57], v[28:31]
	v_mfma_f32_16x16x32_bf16 v[16:19], v[42:45], v[58:61], v[16:19]
	v_mfma_f32_16x16x32_bf16 v[20:23], v[62:65], v[66:69], v[20:23]
	v_mfma_f32_16x16x32_bf16 v[24:27], v[62:65], v[70:73], v[24:27]
	s_waitcnt lgkmcnt(11)
	v_mfma_f32_16x16x32_bf16 v[28:31], v[62:65], v[74:77], v[28:31]
	s_waitcnt lgkmcnt(10)
	v_mfma_f32_16x16x32_bf16 v[16:19], v[62:65], v[78:81], v[16:19]
	s_waitcnt lgkmcnt(3)
	v_mfma_f32_16x16x32_bf16 v[20:23], v[82:85], v[86:89], v[20:23]
	v_lshl_add_u32 v87, v207, 4, s9
	v_lshlrev_b32_e32 v86, 2, v207
	v_or_b32_e32 v38, s0, v86
	s_waitcnt lgkmcnt(2)
	v_mfma_f32_16x16x32_bf16 v[24:27], v[82:85], v[90:93], v[24:27]
	v_lshlrev_b32_e32 v38, 2, v38
	s_waitcnt lgkmcnt(1)
	v_mfma_f32_16x16x32_bf16 v[28:31], v[82:85], v[94:97], v[28:31]
	s_waitcnt lgkmcnt(0)
	v_mfma_f32_16x16x32_bf16 v[16:19], v[82:85], v[98:101], v[16:19]
	s_nop 2
	ds_write2_b32 v34, v20, v24 offset1:16
	ds_write2_b32 v34, v21, v25 offset0:64 offset1:80
	ds_write2_b32 v34, v22, v26 offset0:128 offset1:144
	ds_write2_b32 v34, v23, v27 offset0:192 offset1:208
	s_nop 0
	ds_write2_b32 v34, v28, v16 offset0:32 offset1:48
	ds_write2_b32 v34, v29, v17 offset0:96 offset1:112
	ds_write2_b32 v34, v30, v18 offset0:160 offset1:176
	ds_write2_b32 v34, v31, v19 offset0:224 offset1:240
	s_waitcnt lgkmcnt(0)
	ds_read_b128 v[16:19], v87 offset:61440
	ds_read_b128 v[20:23], v87 offset:62464
	ds_read_b128 v[24:27], v87 offset:63488
	ds_read_b128 v[28:31], v87 offset:64512
	s_waitcnt lgkmcnt(3)
	buffer_store_dwordx4 v[16:19], v38, s[20:23], 0 offen sc1
	s_waitcnt lgkmcnt(2)
	buffer_store_dwordx4 v[20:23], v38, s[20:23], 0 offen offset:1024 sc1
	s_waitcnt lgkmcnt(1)
	buffer_store_dwordx4 v[24:27], v38, s[20:23], 0 offen offset:2048 sc1
	s_waitcnt lgkmcnt(0)
	buffer_store_dwordx4 v[28:31], v38, s[20:23], 0 offen offset:3072 sc1
	s_waitcnt vmcnt(7)
	v_lshlrev_b32_e32 v16, 16, v12
	v_and_b32_e32 v18, 0xffff0000, v12
	v_mul_f32_e32 v17, v103, v16
	v_mul_f32_e32 v12, v103, v18
	v_cvt_pk_bf16_f32 v12, v17, v12
	v_lshlrev_b32_e32 v17, 16, v13
	v_and_b32_e32 v20, 0xffff0000, v13
	v_mul_f32_e32 v19, v103, v17
	v_mul_f32_e32 v13, v103, v20
	v_cvt_pk_bf16_f32 v13, v19, v13
	v_lshlrev_b32_e32 v19, 16, v14
	v_and_b32_e32 v22, 0xffff0000, v14
	v_mul_f32_e32 v21, v103, v19
	v_mul_f32_e32 v14, v103, v22
	v_cvt_pk_bf16_f32 v14, v21, v14
	v_lshlrev_b32_e32 v21, 16, v15
	v_and_b32_e32 v24, 0xffff0000, v15
	v_mul_f32_e32 v23, v103, v21
	v_mul_f32_e32 v15, v103, v24
	v_cvt_pk_bf16_f32 v15, v23, v15
	s_waitcnt lgkmcnt(0)
	s_barrier
	ds_write_b128 v105, v[12:15]
	v_mul_f32_e32 v12, v104, v16
	v_mul_f32_e32 v13, v104, v18
	v_cvt_pk_bf16_f32 v12, v12, v13
	v_mul_f32_e32 v13, v104, v17
	v_mul_f32_e32 v14, v104, v20
	v_cvt_pk_bf16_f32 v13, v13, v14
	v_mul_f32_e32 v14, v104, v19
	v_mul_f32_e32 v15, v104, v22
	v_cvt_pk_bf16_f32 v14, v14, v15
	v_mul_f32_e32 v15, v104, v21
	v_mul_f32_e32 v16, v104, v24
	v_cvt_pk_bf16_f32 v15, v15, v16
	ds_write_b128 v105, v[12:15] offset:20480
	s_waitcnt vmcnt(6)
	ds_write_b128 v105, v[8:11] offset:40960
	s_waitcnt vmcnt(5)
	v_lshlrev_b32_e32 v8, 16, v4
	v_and_b32_e32 v10, 0xffff0000, v4
	v_mul_f32_e32 v9, v35, v8
	v_mul_f32_e32 v4, v35, v10
	v_cvt_pk_bf16_f32 v4, v9, v4
	v_lshlrev_b32_e32 v9, 16, v5
	v_and_b32_e32 v12, 0xffff0000, v5
	v_mul_f32_e32 v11, v35, v9
	v_mul_f32_e32 v5, v35, v12
	v_cvt_pk_bf16_f32 v5, v11, v5
	v_lshlrev_b32_e32 v11, 16, v6
	v_and_b32_e32 v14, 0xffff0000, v6
	v_mul_f32_e32 v13, v35, v11
	v_mul_f32_e32 v6, v35, v14
	v_cvt_pk_bf16_f32 v6, v13, v6
	v_lshlrev_b32_e32 v13, 16, v7
	v_and_b32_e32 v16, 0xffff0000, v7
	v_mul_f32_e32 v15, v35, v13
	v_mul_f32_e32 v7, v35, v16
	v_cvt_pk_bf16_f32 v7, v15, v7
	ds_write_b128 v37, v[4:7]
	v_mul_f32_e32 v4, v32, v8
	v_mul_f32_e32 v5, v32, v10
	v_cvt_pk_bf16_f32 v4, v4, v5
	v_mul_f32_e32 v5, v32, v9
	v_mul_f32_e32 v6, v32, v12
	v_cvt_pk_bf16_f32 v5, v5, v6
	v_mul_f32_e32 v6, v32, v11
	v_mul_f32_e32 v7, v32, v14
	v_cvt_pk_bf16_f32 v6, v6, v7
	v_mul_f32_e32 v7, v32, v13
	v_mul_f32_e32 v8, v32, v16
	v_cvt_pk_bf16_f32 v7, v7, v8
	ds_write_b128 v37, v[4:7] offset:20480
	s_waitcnt vmcnt(4)
	ds_write_b128 v37, v[0:3] offset:40960
	s_waitcnt lgkmcnt(0)
	s_barrier
	ds_read_b64_tr_b16 v[0:1], v106 offset:40960
	ds_read_b64_tr_b16 v[2:3], v106 offset:41600
	ds_read_b64_tr_b16 v[4:5], v107
	ds_read_b64_tr_b16 v[8:9], v107 offset:32
	ds_read_b64_tr_b16 v[6:7], v107 offset:640
	ds_read_b64_tr_b16 v[10:11], v107 offset:672
	ds_read_b64_tr_b16 v[12:13], v107 offset:64
	ds_read_b64_tr_b16 v[16:17], v107 offset:96
	ds_read_b64_tr_b16 v[14:15], v107 offset:704
	ds_read_b64_tr_b16 v[18:19], v107 offset:736
	ds_read_b64_tr_b16 v[20:21], v108 offset:40960
	ds_read_b64_tr_b16 v[22:23], v108 offset:41600
	ds_read_b64_tr_b16 v[24:25], v109
	ds_read_b64_tr_b16 v[28:29], v109 offset:32
	ds_read_b64_tr_b16 v[38:39], v109 offset:64
	ds_read_b64_tr_b16 v[42:43], v109 offset:96
	ds_read_b64_tr_b16 v[26:27], v109 offset:640
	ds_read_b64_tr_b16 v[30:31], v109 offset:672
	ds_read_b64_tr_b16 v[40:41], v109 offset:704
	ds_read_b64_tr_b16 v[44:45], v109 offset:736
	ds_read_b64_tr_b16 v[46:47], v110 offset:40960
	ds_read_b64_tr_b16 v[48:49], v110 offset:41600
	ds_read_b64_tr_b16 v[50:51], v111
	ds_read_b64_tr_b16 v[54:55], v111 offset:32
	ds_read_b64_tr_b16 v[52:53], v111 offset:640
	ds_read_b64_tr_b16 v[56:57], v111 offset:672
	ds_read_b64_tr_b16 v[58:59], v111 offset:64
	ds_read_b64_tr_b16 v[62:63], v111 offset:96
	ds_read_b64_tr_b16 v[60:61], v111 offset:704
	ds_read_b64_tr_b16 v[64:65], v111 offset:736
	ds_read_b64_tr_b16 v[66:67], v112 offset:40960
	ds_read_b64_tr_b16 v[68:69], v112 offset:41600
	ds_read_b64_tr_b16 v[70:71], v113
	ds_read_b64_tr_b16 v[74:75], v113 offset:32
	ds_read_b64_tr_b16 v[78:79], v113 offset:64
	ds_read_b64_tr_b16 v[82:83], v113 offset:96
	ds_read_b64_tr_b16 v[72:73], v113 offset:640
	ds_read_b64_tr_b16 v[76:77], v113 offset:672
	ds_read_b64_tr_b16 v[80:81], v113 offset:704
	ds_read_b64_tr_b16 v[84:85], v113 offset:736
	s_waitcnt lgkmcnt(14)
	v_mfma_f32_16x16x32_bf16 v[4:7], v[0:3], v[4:7], 0
	s_add_i32 s17, s17, s8
	s_lshl_b32 s0, s17, 13
	s_add_i32 s0, s0, s19
	v_mfma_f32_16x16x32_bf16 v[8:11], v[0:3], v[8:11], 0
	s_and_b32 s8, s10, 0x7fffffc
	s_mov_b32 s95, s12
	v_mfma_f32_16x16x32_bf16 v[12:15], v[0:3], v[12:15], 0
	v_mfma_f32_16x16x32_bf16 v[0:3], v[0:3], v[16:19], 0
	v_or_b32_e32 v16, s0, v86
	s_lshl_b32 s0, s5, 4
	s_add_i32 s0, s0, s8
	v_mfma_f32_16x16x32_bf16 v[4:7], v[20:23], v[24:27], v[4:7]
	s_or_b32 s0, s0, s11
	v_lshlrev_b32_e32 v16, 2, v16
	s_lshl_b32 s8, s0, 4
	v_mfma_f32_16x16x32_bf16 v[8:11], v[20:23], v[28:31], v[8:11]
	s_ashr_i32 s9, s8, 31
	s_lshl_b64 s[8:9], s[8:9], 2
	v_readlane_b32 s0, v254, 59
	v_mfma_f32_16x16x32_bf16 v[12:15], v[20:23], v[38:41], v[12:15]
	s_add_u32 s76, s0, s8
	v_readlane_b32 s0, v254, 60
	s_addc_u32 s77, s0, s9
	v_mfma_f32_16x16x32_bf16 v[0:3], v[20:23], v[42:45], v[0:3]
	s_mov_b64 s[10:11], 0
	v_mfma_f32_16x16x32_bf16 v[4:7], v[46:49], v[50:53], v[4:7]
	v_mfma_f32_16x16x32_bf16 v[8:11], v[46:49], v[54:57], v[8:11]
	s_waitcnt lgkmcnt(11)
	v_mfma_f32_16x16x32_bf16 v[12:15], v[46:49], v[58:61], v[12:15]
	s_waitcnt lgkmcnt(10)
	v_mfma_f32_16x16x32_bf16 v[0:3], v[46:49], v[62:65], v[0:3]
	s_waitcnt lgkmcnt(3)
	v_mfma_f32_16x16x32_bf16 v[4:7], v[66:69], v[70:73], v[4:7]
	s_waitcnt lgkmcnt(2)
	v_mfma_f32_16x16x32_bf16 v[8:11], v[66:69], v[74:77], v[8:11]
	s_waitcnt lgkmcnt(1)
	v_mfma_f32_16x16x32_bf16 v[12:15], v[66:69], v[78:81], v[12:15]
	s_waitcnt lgkmcnt(0)
	v_mfma_f32_16x16x32_bf16 v[0:3], v[66:69], v[82:85], v[0:3]
	s_nop 3
	ds_write2_b32 v34, v4, v8 offset1:16
	ds_write2_b32 v34, v5, v9 offset0:64 offset1:80
	ds_write2_b32 v34, v6, v10 offset0:128 offset1:144
	ds_write2_b32 v34, v7, v11 offset0:192 offset1:208
	ds_write2_b32 v34, v12, v0 offset0:32 offset1:48
	ds_write2_b32 v34, v13, v1 offset0:96 offset1:112
	ds_write2_b32 v34, v14, v2 offset0:160 offset1:176
	ds_write2_b32 v34, v15, v3 offset0:224 offset1:240
	s_waitcnt lgkmcnt(0)
	ds_read_b128 v[0:3], v87 offset:61440
	ds_read_b128 v[4:7], v87 offset:62464
	ds_read_b128 v[8:11], v87 offset:63488
	ds_read_b128 v[12:15], v87 offset:64512
	s_waitcnt lgkmcnt(3)
	buffer_store_dwordx4 v[0:3], v16, s[20:23], 0 offen sc1
	s_waitcnt lgkmcnt(2)
	buffer_store_dwordx4 v[4:7], v16, s[20:23], 0 offen offset:1024 sc1
	s_waitcnt lgkmcnt(1)
	buffer_store_dwordx4 v[8:11], v16, s[20:23], 0 offen offset:2048 sc1
	s_waitcnt lgkmcnt(0)
	buffer_store_dwordx4 v[12:15], v16, s[20:23], 0 offen offset:3072 sc1
	s_waitcnt lgkmcnt(0)

.LBB0_1547:
	s_lshl_b32 s8, s12, 8
	s_add_i32 s8, s8, s80
	s_lshl_b32 s9, s42, 3
	v_or_b32_e32 v150, s8, v151
	s_lshl_b32 s8, s12, 5
	s_add_i32 s9, s9, s81
	s_add_i32 s8, s9, s8
	v_lshrrev_b32_e32 v32, 1, v154
	s_ashr_i32 s9, s8, 31
	v_and_b32_e32 v156, 24, v32
	s_lshl_b32 s0, s13, 5
	s_lshl_b32 s46, s42, 8
	s_lshl_b64 s[8:9], s[8:9], 14
	v_and_b32_e32 v155, 63, v154
	v_or_b32_e32 v32, s0, v156
	s_add_u32 s8, s18, s8
	v_or_b32_e32 v152, s46, v32
	s_addc_u32 s9, s19, s9
	v_lshlrev_b32_e32 v32, 4, v155
	v_lshl_add_u64 v[134:135], s[8:9], 0, v[32:33]
	s_mov_b64 s[8:9], 0x14800000
	v_lshl_add_u64 v[34:35], v[134:135], 0, s[8:9]
	s_mov_b32 s8, 0x14800000
	v_add_co_u32_e32 v136, vcc, s8, v134
	s_barrier
	s_nop 0
	v_addc_co_u32_e32 v137, vcc, 0, v135, vcc
	v_add_co_u32_e32 v134, vcc, 0x14801000, v134
	global_load_dwordx4 v[146:149], v[136:137], off nt
	global_load_dwordx4 v[142:145], v[34:35], off offset:2048 nt
	v_addc_co_u32_e32 v135, vcc, 0, v135, vcc
	global_load_dwordx4 v[138:141], v[134:135], off nt
	s_nop 0
	global_load_dwordx4 v[134:137], v[134:135], off offset:2048 nt
	v_mov_b32_e32 v32, s43
	s_movk_i32 s8, 0xffc0
	v_bfi_b32 v32, s8, v32, v154
	s_movk_i32 s79, 0x100
	v_cmp_gt_i32_e64 s[8:9], s79, v32
	v_mov_b32_e32 v154, 0
	s_and_saveexec_b64 s[34:35], s[8:9]
	v_readlane_b32 s84, v254, 27
	s_mov_b32 s94, s20
	v_readlane_b32 s20, v254, 34
	v_readlane_b32 s85, v254, 28
	v_readlane_b32 s96, v254, 31
	v_readlane_b32 s83, v254, 33
	s_movk_i32 s81, 0xff
	s_mov_b32 s82, 0x10000
	v_readlane_b32 s21, v254, 35
	v_readlane_b32 s22, v254, 36
	v_readlane_b32 s23, v254, 37
	v_readlane_b32 s86, v254, 29
	v_readlane_b32 s87, v254, 30
	s_cbranch_execz .LBB0_1549
	s_ashr_i32 s43, s12, 4
	s_add_i32 s43, s43, 15
	v_add_u32_e32 v158, s46, v32
	s_mul_hi_i32 s47, s43, 0x3000
	s_mulk_i32 s43, 0x3000
	s_add_u32 s46, s18, s43
	v_ashrrev_i32_e32 v159, 31, v158
	s_addc_u32 s47, s19, s47
	v_lshlrev_b64 v[158:159], 2, v[158:159]
	v_lshl_add_u64 v[160:161], s[46:47], 0, v[158:159]
	v_add_co_u32_e32 v160, vcc, 0x102000, v160
	v_lshl_add_u64 v[158:159], s[22:23], 0, v[158:159]
	s_nop 0
	v_addc_co_u32_e32 v161, vcc, 0, v161, vcc
	v_add_co_u32_e32 v158, vcc, 0x3000, v158
	global_load_dword v244, v[160:161], off
	s_nop 0
	v_addc_co_u32_e32 v159, vcc, 0, v159, vcc
	global_load_dword v245, v[158:159], off
.LBB0_1549:
	s_or_b64 exec, exec, s[34:35]
	v_mul_f32_e32 v157, v131, v131
	v_mul_f32_e32 v158, v133, v133
	v_fmac_f32_e32 v157, v130, v130
	v_fmac_f32_e32 v158, v132, v132
	v_add_f32_e32 v157, v157, v158
	v_mul_f32_e32 v158, v127, v127
	v_fmac_f32_e32 v158, v126, v126
	v_add_f32_e32 v157, v158, v157
	v_mul_f32_e32 v158, v129, v129
	v_fmac_f32_e32 v158, v128, v128
	v_add_f32_e32 v157, v158, v157
	v_mul_f32_e32 v158, v87, v87
	v_mul_f32_e32 v159, v89, v89
	v_fmac_f32_e32 v158, v86, v86
	v_fmac_f32_e32 v159, v88, v88
	v_add_f32_e32 v158, v158, v159
	v_mul_f32_e32 v159, v79, v79
	v_fmac_f32_e32 v159, v78, v78
	v_add_f32_e32 v158, v159, v158
	v_mul_f32_e32 v159, v81, v81
	v_fmac_f32_e32 v159, v80, v80
	v_add_f32_e32 v158, v159, v158
	v_mul_f32_e32 v159, v123, v123
	v_mul_f32_e32 v160, v125, v125
	v_fmac_f32_e32 v159, v122, v122
	v_fmac_f32_e32 v160, v124, v124
	v_add_f32_e32 v159, v159, v160
	v_mul_f32_e32 v160, v119, v119
	v_fmac_f32_e32 v160, v118, v118
	v_add_f32_e32 v159, v160, v159
	v_mul_f32_e32 v160, v121, v121
	v_fmac_f32_e32 v160, v120, v120
	v_add_f32_e32 v159, v160, v159
	v_mul_f32_e32 v160, v75, v75
	v_mul_f32_e32 v161, v77, v77
	v_fmac_f32_e32 v160, v74, v74
	v_fmac_f32_e32 v161, v76, v76
	v_add_f32_e32 v160, v160, v161
	v_mul_f32_e32 v161, v67, v67
	v_fmac_f32_e32 v161, v66, v66
	v_add_f32_e32 v160, v161, v160
	v_mul_f32_e32 v161, v69, v69
	v_fmac_f32_e32 v161, v68, v68
	v_add_f32_e32 v160, v161, v160
	v_mul_f32_e32 v161, v115, v115
	v_mul_f32_e32 v162, v117, v117
	v_fmac_f32_e32 v161, v114, v114
	v_fmac_f32_e32 v162, v116, v116
	v_add_f32_e32 v161, v161, v162
	v_mul_f32_e32 v162, v111, v111
	v_fmac_f32_e32 v162, v110, v110
	v_add_f32_e32 v161, v162, v161
	v_mul_f32_e32 v162, v113, v113
	v_fmac_f32_e32 v162, v112, v112
	v_add_f32_e32 v161, v162, v161
	v_mul_f32_e32 v162, v59, v59
	v_mul_f32_e32 v163, v61, v61
	v_fmac_f32_e32 v162, v58, v58
	v_fmac_f32_e32 v163, v60, v60
	v_add_f32_e32 v162, v162, v163
	v_mul_f32_e32 v163, v55, v55
	v_fmac_f32_e32 v163, v54, v54
	v_add_f32_e32 v162, v163, v162
	v_mul_f32_e32 v163, v57, v57
	v_fmac_f32_e32 v163, v56, v56
	v_add_f32_e32 v162, v163, v162
	v_mul_f32_e32 v163, v107, v107
	v_mul_f32_e32 v164, v109, v109
	v_fmac_f32_e32 v163, v106, v106
	v_fmac_f32_e32 v164, v108, v108
	v_add_f32_e32 v163, v163, v164
	v_mul_f32_e32 v164, v103, v103
	v_fmac_f32_e32 v164, v102, v102
	v_add_f32_e32 v163, v164, v163
	v_mul_f32_e32 v164, v105, v105
	v_fmac_f32_e32 v164, v104, v104
	v_add_f32_e32 v163, v164, v163
	v_mul_f32_e32 v164, v43, v43
	v_mul_f32_e32 v165, v45, v45
	v_fmac_f32_e32 v164, v42, v42
	v_fmac_f32_e32 v165, v44, v44
	v_add_f32_e32 v164, v164, v165
	v_mul_f32_e32 v165, v39, v39
	v_fmac_f32_e32 v165, v38, v38
	v_add_f32_e32 v164, v165, v164
	v_mul_f32_e32 v165, v41, v41
	v_fmac_f32_e32 v165, v40, v40
	v_add_f32_e32 v164, v165, v164
	v_mul_f32_e32 v165, v99, v99
	v_mul_f32_e32 v166, v101, v101
	v_fmac_f32_e32 v165, v98, v98
	v_fmac_f32_e32 v166, v100, v100
	v_add_f32_e32 v165, v165, v166
	v_mul_f32_e32 v166, v95, v95
	v_fmac_f32_e32 v166, v94, v94
	v_add_f32_e32 v165, v166, v165
	v_mul_f32_e32 v166, v97, v97
	v_fmac_f32_e32 v166, v96, v96
	v_add_f32_e32 v165, v166, v165
	v_mul_f32_e32 v166, v29, v29
	v_mul_f32_e32 v167, v31, v31
	v_fmac_f32_e32 v166, v28, v28
	v_fmac_f32_e32 v167, v30, v30
	v_add_f32_e32 v166, v166, v167
	v_mul_f32_e32 v167, v25, v25
	v_fmac_f32_e32 v167, v24, v24
	v_add_f32_e32 v166, v167, v166
	v_mul_f32_e32 v167, v27, v27
	v_fmac_f32_e32 v167, v26, v26
	v_add_f32_e32 v166, v167, v166
	v_mul_f32_e32 v167, v91, v91
	v_mul_f32_e32 v168, v93, v93
	v_fmac_f32_e32 v167, v90, v90
	v_fmac_f32_e32 v168, v92, v92
	v_add_f32_e32 v167, v167, v168
	v_mul_f32_e32 v168, v83, v83
	v_fmac_f32_e32 v168, v82, v82
	v_add_f32_e32 v167, v168, v167
	v_mul_f32_e32 v168, v85, v85
	v_fmac_f32_e32 v168, v84, v84
	v_add_f32_e32 v167, v168, v167
	v_mul_f32_e32 v168, v21, v21
	v_mul_f32_e32 v169, v23, v23
	v_fmac_f32_e32 v168, v20, v20
	v_fmac_f32_e32 v169, v22, v22
	v_add_f32_e32 v168, v168, v169
	v_mul_f32_e32 v169, v17, v17
	v_fmac_f32_e32 v169, v16, v16
	v_add_f32_e32 v168, v169, v168
	v_mul_f32_e32 v169, v19, v19
	v_fmac_f32_e32 v169, v18, v18
	v_add_f32_e32 v168, v169, v168
	v_mul_f32_e32 v169, v71, v71
	v_mul_f32_e32 v170, v73, v73
	v_fmac_f32_e32 v169, v70, v70
	v_fmac_f32_e32 v170, v72, v72
	v_add_f32_e32 v169, v169, v170
	v_mul_f32_e32 v170, v63, v63
	v_fmac_f32_e32 v170, v62, v62
	v_add_f32_e32 v157, v158, v157
	v_add_f32_e32 v169, v170, v169
	v_mul_f32_e32 v170, v65, v65
	v_mov_b32_e32 v158, v157
	v_fmac_f32_e32 v170, v64, v64
	s_nop 1
	v_permlane16_swap_b32 v157, v158
	s_nop 1
	v_add_f32_e32 v169, v170, v169
	v_mul_f32_e32 v170, v13, v13
	v_mul_f32_e32 v171, v15, v15
	v_add_f32_e32 v157, v157, v158
	v_add_f32_e32 v159, v160, v159
	v_fmac_f32_e32 v170, v12, v12
	v_fmac_f32_e32 v171, v14, v14
	v_mov_b32_e32 v158, v157
	v_mov_b32_e32 v160, v159
	v_add_f32_e32 v170, v170, v171
	v_mul_f32_e32 v171, v9, v9
	s_nop 1
	v_permlane32_swap_b32 v157, v158
	s_nop 1
	s_nop 1
	v_permlane16_swap_b32 v159, v160
	s_nop 1
	v_fmac_f32_e32 v171, v8, v8
	v_add_f32_e32 v159, v159, v160
	v_add_f32_e32 v161, v162, v161
	v_add_f32_e32 v170, v171, v170
	v_mul_f32_e32 v171, v11, v11
	v_mov_b32_e32 v160, v159
	v_mov_b32_e32 v162, v161
	v_fmac_f32_e32 v171, v10, v10
	s_nop 1
	v_permlane32_swap_b32 v159, v160
	s_nop 1
	s_nop 1
	v_permlane16_swap_b32 v161, v162
	s_nop 1
	v_add_f32_e32 v170, v171, v170
	v_mul_f32_e32 v171, v51, v51
	v_mul_f32_e32 v172, v53, v53
	v_add_f32_e32 v161, v161, v162
	v_add_f32_e32 v163, v164, v163
	v_fmac_f32_e32 v171, v50, v50
	v_fmac_f32_e32 v172, v52, v52
	v_mov_b32_e32 v162, v161
	v_mov_b32_e32 v164, v163
	v_add_f32_e32 v171, v171, v172
	v_mul_f32_e32 v172, v47, v47
	s_nop 1
	v_permlane32_swap_b32 v161, v162
	s_nop 1
	s_nop 1
	v_permlane16_swap_b32 v163, v164
	s_nop 1
	v_fmac_f32_e32 v172, v46, v46
	v_add_f32_e32 v163, v163, v164
	v_add_f32_e32 v165, v166, v165
	v_add_f32_e32 v171, v172, v171
	v_mul_f32_e32 v172, v49, v49
	v_mov_b32_e32 v164, v163
	v_mov_b32_e32 v166, v165
	v_fmac_f32_e32 v172, v48, v48
	s_nop 1
	v_permlane32_swap_b32 v163, v164
	s_nop 1
	s_nop 1
	v_permlane16_swap_b32 v165, v166
	s_nop 1
	v_add_f32_e32 v171, v172, v171
	v_mul_f32_e32 v172, v5, v5
	v_mul_f32_e32 v173, v7, v7
	v_add_f32_e32 v165, v165, v166
	v_add_f32_e32 v167, v168, v167
	v_fmac_f32_e32 v172, v4, v4
	v_fmac_f32_e32 v173, v6, v6
	v_mov_b32_e32 v166, v165
	v_mov_b32_e32 v168, v167
	v_add_f32_e32 v172, v172, v173
	v_mul_f32_e32 v173, v1, v1
	s_nop 1
	v_permlane32_swap_b32 v165, v166
	s_nop 1
	s_nop 1
	v_permlane16_swap_b32 v167, v168
	s_nop 1
	v_fmac_f32_e32 v173, v0, v0
	v_add_f32_e32 v167, v167, v168
	v_add_f32_e32 v169, v170, v169
	v_add_f32_e32 v172, v173, v172
	v_mul_f32_e32 v173, v3, v3
	v_mov_b32_e32 v168, v167
	v_mov_b32_e32 v170, v169
	v_fmac_f32_e32 v173, v2, v2
	s_nop 1
	v_permlane32_swap_b32 v167, v168
	s_nop 1
	s_nop 1
	v_permlane16_swap_b32 v169, v170
	s_nop 1
	v_add_f32_e32 v172, v173, v172
	v_add_f32_e32 v169, v169, v170
	v_add_f32_e32 v171, v172, v171
	v_mov_b32_e32 v170, v169
	v_mov_b32_e32 v172, v171
	s_nop 1
	v_permlane32_swap_b32 v169, v170
	s_nop 1
	s_nop 1
	v_permlane16_swap_b32 v171, v172
	s_nop 1
	s_nop 0
	v_add_f32_e32 v171, v171, v172
	v_mov_b32_e32 v172, v171
	s_nop 1
	v_permlane32_swap_b32 v171, v172
	s_nop 1
	s_and_saveexec_b64 s[34:35], s[8:9]
	s_cbranch_execz .LBB0_1551
	s_waitcnt vmcnt(0)
	v_mul_f32_e32 v154, v244, v245
	v_lshl_add_u32 v173, v32, 2, 0
	ds_write2st64_b32 v173, v154, v33 offset0:24 offset1:28
	ds_write_b32 v173, v33 offset:8192

.LBB0_1637:
	s_lshl_b32 s8, s16, 8
	s_add_i32 s8, s8, s76
	s_lshl_b32 s9, s42, 3
	v_or_b32_e32 v170, s8, v168
	s_lshl_b32 s8, s16, 5
	s_add_i32 s9, s9, s43
	s_add_i32 s8, s9, s8
	v_lshrrev_b32_e32 v32, 1, v152
	s_ashr_i32 s9, s8, 31
	v_and_b32_e32 v153, 24, v32
	s_lshl_b32 s0, s77, 5
	s_lshl_b32 s12, s42, 8
	s_lshl_b64 s[8:9], s[8:9], 14
	v_and_b32_e32 v154, 63, v152
	v_or_b32_e32 v32, s0, v153
	s_add_u32 s8, s18, s8
	v_or_b32_e32 v171, s12, v32
	s_addc_u32 s9, s19, s9
	v_lshlrev_b32_e32 v32, 4, v154
	v_lshl_add_u64 v[150:151], s[8:9], 0, v[32:33]
	s_mov_b64 s[8:9], 0x14800000
	v_lshl_add_u64 v[160:161], v[150:151], 0, s[8:9]
	s_mov_b32 s8, 0x14800000
	v_add_co_u32_e32 v34, vcc, s8, v150
	s_barrier
	s_nop 0
	v_addc_co_u32_e32 v35, vcc, 0, v151, vcc
	global_load_dwordx4 v[146:149], v[34:35], off nt
	global_load_dwordx4 v[142:145], v[160:161], off offset:2048 nt
	v_add_co_u32_e32 v34, vcc, 0x14801000, v150
	v_mov_b32_e32 v32, s17
	s_nop 0
	v_addc_co_u32_e32 v35, vcc, 0, v151, vcc
	global_load_dwordx4 v[138:141], v[34:35], off nt
	global_load_dwordx4 v[134:137], v[34:35], off offset:2048 nt
	s_movk_i32 s8, 0xffc0
	v_bfi_b32 v32, s8, v32, v152
	s_movk_i32 s79, 0x100
	v_cmp_gt_i32_e64 s[8:9], s79, v32
	v_mov_b32_e32 v152, 0
	v_mov_b32_e32 v34, 0
	v_mov_b32_e32 v35, 0
	s_and_saveexec_b64 s[10:11], s[8:9]
	v_readlane_b32 s84, v254, 27
	v_readlane_b32 s85, v254, 28
	v_readlane_b32 s83, v254, 33
	s_movk_i32 s81, 0xff
	s_mov_b32 s82, 0x10000
	v_readlane_b32 s86, v254, 29
	v_readlane_b32 s87, v254, 30
	s_cbranch_execz .LBB0_1639
	s_add_u32 s17, s18, 0x100000
	v_add_u32_e32 v34, s12, v32
	s_addc_u32 s34, s19, 0
	v_readlane_b32 s12, v254, 16
	s_ashr_i32 s43, s16, 4
	s_mul_i32 s35, s12, 5
	s_ashr_i32 s46, s43, 31
	s_add_u32 s12, s43, s35
	s_addc_u32 s13, s46, 0
	s_mulk_i32 s13, 0x3000
	s_mul_hi_u32 s47, s12, 0x3000
	s_add_i32 s47, s47, s13
	s_mulk_i32 s12, 0x3000
	s_add_u32 s12, s17, s12
	v_ashrrev_i32_e32 v35, 31, v34
	s_addc_u32 s13, s34, s47
	v_lshlrev_b64 v[156:157], 2, v[34:35]
	v_lshl_add_u64 v[158:159], s[12:13], 0, v[156:157]
	s_movk_i32 s12, 0x2000
	s_add_i32 s35, s35, 5
	v_add_co_u32_e32 v158, vcc, s12, v158
	s_add_u32 s12, s43, s35
	s_addc_u32 s13, s46, 0
	s_mulk_i32 s13, 0x3000
	s_mul_hi_u32 s35, s12, 0x3000
	s_add_i32 s35, s35, s13
	s_mulk_i32 s12, 0x3000
	s_add_u32 s12, s17, s12
	s_addc_u32 s13, s34, s35
	v_addc_co_u32_e32 v159, vcc, 0, v159, vcc
	v_lshl_add_u64 v[156:157], s[12:13], 0, v[156:157]
	s_movk_i32 s12, 0x1000
	v_add_co_u32_e32 v162, vcc, s12, v156
	global_load_dword v244, v[158:159], off
	s_nop 0
	v_addc_co_u32_e32 v163, vcc, 0, v157, vcc
	global_load_dword v245, v[162:163], off
	v_add_u32_e32 v158, s30, v34
	s_add_i32 s12, s30, 0x400
	v_ashrrev_i32_e32 v159, 31, v158
	v_add_u32_e32 v162, s12, v34
	v_lshl_add_u64 v[158:159], v[158:159], 2, s[22:23]
	v_ashrrev_i32_e32 v163, 31, v162
	global_load_dword v246, v[158:159], off
	v_lshl_add_u64 v[162:163], v[162:163], 2, s[20:21]
	global_load_dword v247, v[162:163], off
	global_load_dword v248, v[156:157], off
.LBB0_1639:
	s_or_b64 exec, exec, s[10:11]
	v_mul_f32_e32 v155, v131, v131
	v_mul_f32_e32 v156, v133, v133
	v_fmac_f32_e32 v155, v130, v130
	v_fmac_f32_e32 v156, v132, v132
	v_add_f32_e32 v155, v155, v156
	v_mul_f32_e32 v156, v127, v127
	v_fmac_f32_e32 v156, v126, v126
	v_add_f32_e32 v155, v156, v155
	v_mul_f32_e32 v156, v129, v129
	v_fmac_f32_e32 v156, v128, v128
	v_add_f32_e32 v155, v156, v155
	v_mul_f32_e32 v156, v91, v91
	v_mul_f32_e32 v157, v93, v93
	v_fmac_f32_e32 v156, v90, v90
	v_fmac_f32_e32 v157, v92, v92
	v_add_f32_e32 v156, v156, v157
	v_mul_f32_e32 v157, v83, v83
	v_fmac_f32_e32 v157, v82, v82
	v_add_f32_e32 v156, v157, v156
	v_mul_f32_e32 v157, v85, v85
	v_fmac_f32_e32 v157, v84, v84
	v_add_f32_e32 v156, v157, v156
	v_mul_f32_e32 v157, v123, v123
	v_mul_f32_e32 v158, v125, v125
	v_fmac_f32_e32 v157, v122, v122
	v_fmac_f32_e32 v158, v124, v124
	v_add_f32_e32 v157, v157, v158
	v_mul_f32_e32 v158, v119, v119
	v_fmac_f32_e32 v158, v118, v118
	v_add_f32_e32 v157, v158, v157
	v_mul_f32_e32 v158, v121, v121
	v_fmac_f32_e32 v158, v120, v120
	v_add_f32_e32 v157, v158, v157
	v_mul_f32_e32 v158, v75, v75
	v_mul_f32_e32 v159, v77, v77
	v_fmac_f32_e32 v158, v74, v74
	v_fmac_f32_e32 v159, v76, v76
	v_add_f32_e32 v158, v158, v159
	v_mul_f32_e32 v159, v67, v67
	v_fmac_f32_e32 v159, v66, v66
	v_add_f32_e32 v158, v159, v158
	v_mul_f32_e32 v159, v69, v69
	v_fmac_f32_e32 v159, v68, v68
	v_add_f32_e32 v158, v159, v158
	v_mul_f32_e32 v159, v115, v115
	v_mul_f32_e32 v162, v117, v117
	v_fmac_f32_e32 v159, v114, v114
	v_fmac_f32_e32 v162, v116, v116
	v_add_f32_e32 v159, v159, v162
	v_mul_f32_e32 v162, v111, v111
	v_fmac_f32_e32 v162, v110, v110
	v_add_f32_e32 v159, v162, v159
	v_mul_f32_e32 v162, v113, v113
	v_fmac_f32_e32 v162, v112, v112
	v_add_f32_e32 v159, v162, v159
	v_mul_f32_e32 v162, v59, v59
	v_mul_f32_e32 v163, v61, v61
	v_fmac_f32_e32 v162, v58, v58
	v_fmac_f32_e32 v163, v60, v60
	v_add_f32_e32 v162, v162, v163
	v_mul_f32_e32 v163, v55, v55
	v_fmac_f32_e32 v163, v54, v54
	v_add_f32_e32 v162, v163, v162
	v_mul_f32_e32 v163, v57, v57
	v_fmac_f32_e32 v163, v56, v56
	v_add_f32_e32 v162, v163, v162
	v_mul_f32_e32 v163, v107, v107
	v_mul_f32_e32 v164, v109, v109
	v_fmac_f32_e32 v163, v106, v106
	v_fmac_f32_e32 v164, v108, v108
	v_add_f32_e32 v163, v163, v164
	v_mul_f32_e32 v164, v103, v103
	v_fmac_f32_e32 v164, v102, v102
	v_add_f32_e32 v163, v164, v163
	v_mul_f32_e32 v164, v105, v105
	v_fmac_f32_e32 v164, v104, v104
	v_add_f32_e32 v163, v164, v163
	v_mul_f32_e32 v164, v43, v43
	v_mul_f32_e32 v165, v45, v45
	v_fmac_f32_e32 v164, v42, v42
	v_fmac_f32_e32 v165, v44, v44
	v_add_f32_e32 v164, v164, v165
	v_mul_f32_e32 v165, v39, v39
	v_fmac_f32_e32 v165, v38, v38
	v_add_f32_e32 v164, v165, v164
	v_mul_f32_e32 v165, v41, v41
	v_fmac_f32_e32 v165, v40, v40
	v_add_f32_e32 v164, v165, v164
	v_mul_f32_e32 v165, v99, v99
	v_mul_f32_e32 v166, v101, v101
	v_fmac_f32_e32 v165, v98, v98
	v_fmac_f32_e32 v166, v100, v100
	v_add_f32_e32 v165, v165, v166
	v_mul_f32_e32 v166, v95, v95
	v_fmac_f32_e32 v166, v94, v94
	v_add_f32_e32 v165, v166, v165
	v_mul_f32_e32 v166, v97, v97
	v_fmac_f32_e32 v166, v96, v96
	v_add_f32_e32 v165, v166, v165
	v_mul_f32_e32 v166, v29, v29
	v_mul_f32_e32 v167, v31, v31
	v_fmac_f32_e32 v166, v28, v28
	v_fmac_f32_e32 v167, v30, v30
	v_add_f32_e32 v166, v166, v167
	v_mul_f32_e32 v167, v25, v25
	v_fmac_f32_e32 v167, v24, v24
	v_add_f32_e32 v166, v167, v166
	v_mul_f32_e32 v167, v27, v27
	v_fmac_f32_e32 v167, v26, v26
	v_add_f32_e32 v166, v167, v166
	v_mul_f32_e32 v167, v87, v87
	v_mul_f32_e32 v172, v89, v89
	v_fmac_f32_e32 v167, v86, v86
	v_fmac_f32_e32 v172, v88, v88
	v_add_f32_e32 v167, v167, v172
	v_mul_f32_e32 v172, v79, v79
	v_fmac_f32_e32 v172, v78, v78
	v_add_f32_e32 v167, v172, v167
	v_mul_f32_e32 v172, v81, v81
	v_fmac_f32_e32 v172, v80, v80
	v_add_f32_e32 v167, v172, v167
	v_mul_f32_e32 v172, v21, v21
	v_mul_f32_e32 v173, v23, v23
	v_fmac_f32_e32 v172, v20, v20
	v_fmac_f32_e32 v173, v22, v22
	v_add_f32_e32 v172, v172, v173
	v_mul_f32_e32 v173, v17, v17
	v_fmac_f32_e32 v173, v16, v16
	v_add_f32_e32 v172, v173, v172
	v_mul_f32_e32 v173, v19, v19
	v_fmac_f32_e32 v173, v18, v18
	v_add_f32_e32 v172, v173, v172
	v_mul_f32_e32 v173, v71, v71
	v_mul_f32_e32 v174, v73, v73
	v_fmac_f32_e32 v173, v70, v70
	v_fmac_f32_e32 v174, v72, v72
	v_add_f32_e32 v173, v173, v174
	v_mul_f32_e32 v174, v63, v63
	v_fmac_f32_e32 v174, v62, v62
	v_add_f32_e32 v155, v156, v155
	v_add_f32_e32 v173, v174, v173
	v_mul_f32_e32 v174, v65, v65
	v_mov_b32_e32 v156, v155
	v_fmac_f32_e32 v174, v64, v64
	s_nop 1
	v_permlane16_swap_b32 v155, v156
	s_nop 1
	v_add_f32_e32 v173, v174, v173
	v_mul_f32_e32 v174, v13, v13
	v_mul_f32_e32 v175, v15, v15
	v_add_f32_e32 v155, v155, v156
	v_add_f32_e32 v157, v158, v157
	v_fmac_f32_e32 v174, v12, v12
	v_fmac_f32_e32 v175, v14, v14
	v_mov_b32_e32 v156, v155
	v_mov_b32_e32 v158, v157
	v_add_f32_e32 v174, v174, v175
	v_mul_f32_e32 v175, v9, v9
	s_nop 1
	v_permlane32_swap_b32 v155, v156
	s_nop 1
	s_nop 1
	v_permlane16_swap_b32 v157, v158
	s_nop 1
	v_fmac_f32_e32 v175, v8, v8
	v_add_f32_e32 v157, v157, v158
	v_add_f32_e32 v159, v162, v159
	v_add_f32_e32 v174, v175, v174
	v_mul_f32_e32 v175, v11, v11
	v_mov_b32_e32 v158, v157
	v_mov_b32_e32 v162, v159
	v_fmac_f32_e32 v175, v10, v10
	s_nop 1
	v_permlane32_swap_b32 v157, v158
	s_nop 1
	s_nop 1
	v_permlane16_swap_b32 v159, v162
	s_nop 1
	v_add_f32_e32 v174, v175, v174
	v_mul_f32_e32 v175, v51, v51
	v_mul_f32_e32 v176, v53, v53
	v_add_f32_e32 v159, v159, v162
	v_add_f32_e32 v163, v164, v163
	v_fmac_f32_e32 v175, v50, v50
	v_fmac_f32_e32 v176, v52, v52
	v_mov_b32_e32 v162, v159
	v_mov_b32_e32 v164, v163
	v_add_f32_e32 v175, v175, v176
	v_mul_f32_e32 v176, v47, v47
	s_nop 1
	v_permlane32_swap_b32 v159, v162
	s_nop 1
	s_nop 1
	v_permlane16_swap_b32 v163, v164
	s_nop 1
	v_fmac_f32_e32 v176, v46, v46
	v_add_f32_e32 v163, v163, v164
	v_add_f32_e32 v165, v166, v165
	v_add_f32_e32 v175, v176, v175
	v_mul_f32_e32 v176, v49, v49
	v_mov_b32_e32 v164, v163
	v_mov_b32_e32 v166, v165
	v_fmac_f32_e32 v176, v48, v48
	s_nop 1
	v_permlane32_swap_b32 v163, v164
	s_nop 1
	s_nop 1
	v_permlane16_swap_b32 v165, v166
	s_nop 1
	v_add_f32_e32 v175, v176, v175
	v_mul_f32_e32 v176, v5, v5
	v_mul_f32_e32 v177, v7, v7
	v_add_f32_e32 v165, v165, v166
	v_add_f32_e32 v167, v172, v167
	v_fmac_f32_e32 v176, v4, v4
	v_fmac_f32_e32 v177, v6, v6
	v_mov_b32_e32 v166, v165
	v_mov_b32_e32 v172, v167
	v_add_f32_e32 v176, v176, v177
	v_mul_f32_e32 v177, v1, v1
	s_nop 1
	v_permlane32_swap_b32 v165, v166
	s_nop 1
	s_nop 1
	v_permlane16_swap_b32 v167, v172
	s_nop 1
	v_fmac_f32_e32 v177, v0, v0
	v_add_f32_e32 v167, v167, v172
	v_add_f32_e32 v173, v174, v173
	v_add_f32_e32 v176, v177, v176
	v_mul_f32_e32 v177, v3, v3
	v_mov_b32_e32 v172, v167
	v_mov_b32_e32 v174, v173
	v_fmac_f32_e32 v177, v2, v2
	s_nop 1
	v_permlane32_swap_b32 v167, v172
	s_nop 1
	s_nop 1
	v_permlane16_swap_b32 v173, v174
	s_nop 1
	v_add_f32_e32 v176, v177, v176
	v_add_f32_e32 v173, v173, v174
	v_add_f32_e32 v175, v176, v175
	v_mov_b32_e32 v174, v173
	v_mov_b32_e32 v176, v175
	s_nop 1
	v_permlane32_swap_b32 v173, v174
	s_nop 1
	s_nop 1
	v_permlane16_swap_b32 v175, v176
	s_nop 1
	s_nop 0
	v_add_f32_e32 v175, v175, v176
	v_mov_b32_e32 v176, v175
	s_nop 1
	v_permlane32_swap_b32 v175, v176
	s_nop 1
	s_and_saveexec_b64 s[10:11], s[8:9]
	s_cbranch_execz .LBB0_1641
	s_waitcnt vmcnt(0)
	v_add_f32_e32 v34, 1.0, v245
	v_mul_f32_e32 v34, v34, v247
	v_mul_f32_e32 v35, v244, v246
	v_mov_b32_e32 v152, v248
	v_lshl_add_u32 v177, v32, 2, 0
	ds_write2st64_b32 v177, v35, v34 offset0:24 offset1:28
	ds_write_b32 v177, v152 offset:8192

.LBB0_1748:
	v_lshrrev_b32_e32 v32, 1, v156
	s_lshl_b32 s5, s46, 8
	v_and_b32_e32 v157, 24, v32
	s_lshl_b32 s0, s75, 5
	s_add_i32 s5, s5, s74
	v_or_b32_e32 v150, s5, v170
	s_lshl_b32 s5, s12, 8
	v_or_b32_e32 v32, s0, v157
	v_or_b32_e32 v152, s5, v32
	s_barrier
	v_mov_b32_e32 v32, s13
	v_ashrrev_i32_e32 v153, 31, v152
	v_ashrrev_i32_e32 v151, 31, v150
	v_lshl_add_u64 v[134:135], v[152:153], 2, s[24:25]
	v_lshlrev_b64 v[168:169], 12, v[150:151]
	v_lshl_add_u64 v[34:35], v[134:135], 0, v[168:169]
	global_load_dwordx4 v[142:145], v[34:35], off offset:16 nt
	global_load_dwordx4 v[146:149], v[34:35], off nt
	v_add_u32_e32 v34, 16, v150
	v_ashrrev_i32_e32 v35, 31, v34
	v_lshlrev_b64 v[166:167], 12, v[34:35]
	v_lshl_add_u64 v[138:139], v[134:135], 0, v[166:167]
	global_load_dwordx4 v[134:137], v[138:139], off offset:16 nt
	s_nop 0
	global_load_dwordx4 v[138:141], v[138:139], off nt
	s_movk_i32 s6, 0xffc0
	v_bfi_b32 v32, s6, v32, v156
	s_movk_i32 s79, 0x100
	v_cmp_gt_i32_e64 s[6:7], s79, v32
	v_mov_b32_e32 v35, 0
	v_mov_b32_e32 v154, 0
	v_mov_b32_e32 v155, 0
	s_and_saveexec_b64 s[8:9], s[6:7]
	v_readlane_b32 s83, v254, 33
	s_movk_i32 s81, 0xff
	s_mov_b32 s82, 0x10000
	s_cbranch_execz .LBB0_1750
	v_add_u32_e32 v154, s5, v32
	s_ashr_i32 s5, s46, 4
	s_mul_hi_i32 s11, s5, 0x3000
	s_mulk_i32 s5, 0x3000
	s_add_u32 s10, s18, s5
	v_ashrrev_i32_e32 v155, 31, v154
	s_addc_u32 s11, s19, s11
	v_lshlrev_b64 v[154:155], 2, v[154:155]
	v_lshl_add_u64 v[158:159], s[10:11], 0, v[154:155]
	v_add_co_u32_e32 v160, vcc, 0x102000, v158
	v_lshl_add_u64 v[162:163], s[22:23], 0, v[154:155]
	s_nop 0
	v_addc_co_u32_e32 v161, vcc, 0, v159, vcc
	v_add_co_u32_e32 v164, vcc, 0x110000, v158
	v_lshl_add_u64 v[154:155], s[20:21], 0, v[154:155]
	s_nop 0
	v_addc_co_u32_e32 v165, vcc, 0, v159, vcc
	v_add_co_u32_e32 v154, vcc, 0x1000, v154
	global_load_dword v244, v[162:163], off
	s_nop 0
	v_addc_co_u32_e32 v155, vcc, 0, v155, vcc
	global_load_dword v245, v[154:155], off
	v_add_co_u32_e32 v154, vcc, 0x10f000, v158
	global_load_dword v246, v[160:161], off
	s_nop 0
	v_addc_co_u32_e32 v155, vcc, 0, v159, vcc
	global_load_dword v247, v[154:155], off
	global_load_dword v248, v[164:165], off
.LBB0_1750:
	s_or_b64 exec, exec, s[8:9]
	v_mul_f32_e32 v158, v131, v131
	v_mul_f32_e32 v159, v133, v133
	v_fmac_f32_e32 v158, v130, v130
	v_fmac_f32_e32 v159, v132, v132
	v_add_f32_e32 v158, v158, v159
	v_mul_f32_e32 v159, v127, v127
	v_fmac_f32_e32 v159, v126, v126
	v_add_f32_e32 v158, v159, v158
	v_mul_f32_e32 v159, v129, v129
	v_fmac_f32_e32 v159, v128, v128
	v_add_f32_e32 v158, v159, v158
	v_mul_f32_e32 v159, v91, v91
	v_mul_f32_e32 v160, v93, v93
	v_fmac_f32_e32 v159, v90, v90
	v_fmac_f32_e32 v160, v92, v92
	v_add_f32_e32 v159, v159, v160
	v_mul_f32_e32 v160, v87, v87
	v_fmac_f32_e32 v160, v86, v86
	v_add_f32_e32 v159, v160, v159
	v_mul_f32_e32 v160, v89, v89
	v_fmac_f32_e32 v160, v88, v88
	v_add_f32_e32 v159, v160, v159
	v_mul_f32_e32 v160, v123, v123
	v_mul_f32_e32 v161, v125, v125
	v_fmac_f32_e32 v160, v122, v122
	v_fmac_f32_e32 v161, v124, v124
	v_add_f32_e32 v160, v160, v161
	v_mul_f32_e32 v161, v119, v119
	v_fmac_f32_e32 v161, v118, v118
	v_add_f32_e32 v160, v161, v160
	v_mul_f32_e32 v161, v121, v121
	v_fmac_f32_e32 v161, v120, v120
	v_add_f32_e32 v160, v161, v160
	v_mul_f32_e32 v161, v79, v79
	v_mul_f32_e32 v162, v81, v81
	v_fmac_f32_e32 v161, v78, v78
	v_fmac_f32_e32 v162, v80, v80
	v_add_f32_e32 v161, v161, v162
	v_mul_f32_e32 v162, v71, v71
	v_fmac_f32_e32 v162, v70, v70
	v_add_f32_e32 v161, v162, v161
	v_mul_f32_e32 v162, v73, v73
	v_fmac_f32_e32 v162, v72, v72
	v_add_f32_e32 v161, v162, v161
	v_mul_f32_e32 v162, v115, v115
	v_mul_f32_e32 v163, v117, v117
	v_fmac_f32_e32 v162, v114, v114
	v_fmac_f32_e32 v163, v116, v116
	v_add_f32_e32 v162, v162, v163
	v_mul_f32_e32 v163, v111, v111
	v_fmac_f32_e32 v163, v110, v110
	v_add_f32_e32 v162, v163, v162
	v_mul_f32_e32 v163, v113, v113
	v_fmac_f32_e32 v163, v112, v112
	v_add_f32_e32 v162, v163, v162
	v_mul_f32_e32 v163, v63, v63
	v_mul_f32_e32 v164, v65, v65
	v_fmac_f32_e32 v163, v62, v62
	v_fmac_f32_e32 v164, v64, v64
	v_add_f32_e32 v163, v163, v164
	v_mul_f32_e32 v164, v55, v55
	v_fmac_f32_e32 v164, v54, v54
	v_add_f32_e32 v163, v164, v163
	v_mul_f32_e32 v164, v57, v57
	v_fmac_f32_e32 v164, v56, v56
	v_add_f32_e32 v163, v164, v163
	v_mul_f32_e32 v164, v107, v107
	v_mul_f32_e32 v165, v109, v109
	v_fmac_f32_e32 v164, v106, v106
	v_fmac_f32_e32 v165, v108, v108
	v_add_f32_e32 v164, v164, v165
	v_mul_f32_e32 v165, v103, v103
	v_fmac_f32_e32 v165, v102, v102
	v_add_f32_e32 v164, v165, v164
	v_mul_f32_e32 v165, v105, v105
	v_fmac_f32_e32 v165, v104, v104
	v_add_f32_e32 v164, v165, v164
	v_mul_f32_e32 v165, v51, v51
	v_mul_f32_e32 v172, v53, v53
	v_fmac_f32_e32 v165, v50, v50
	v_fmac_f32_e32 v172, v52, v52
	v_add_f32_e32 v165, v165, v172
	v_mul_f32_e32 v172, v43, v43
	v_fmac_f32_e32 v172, v42, v42
	v_add_f32_e32 v165, v172, v165
	v_mul_f32_e32 v172, v45, v45
	v_fmac_f32_e32 v172, v44, v44
	v_add_f32_e32 v165, v172, v165
	v_mul_f32_e32 v172, v99, v99
	v_mul_f32_e32 v173, v101, v101
	v_fmac_f32_e32 v172, v98, v98
	v_fmac_f32_e32 v173, v100, v100
	v_add_f32_e32 v172, v172, v173
	v_mul_f32_e32 v173, v95, v95
	v_fmac_f32_e32 v173, v94, v94
	v_add_f32_e32 v172, v173, v172
	v_mul_f32_e32 v173, v97, v97
	v_fmac_f32_e32 v173, v96, v96
	v_add_f32_e32 v172, v173, v172
	v_mul_f32_e32 v173, v29, v29
	v_mul_f32_e32 v174, v31, v31
	v_fmac_f32_e32 v173, v28, v28
	v_fmac_f32_e32 v174, v30, v30
	v_add_f32_e32 v173, v173, v174
	v_mul_f32_e32 v174, v25, v25
	v_fmac_f32_e32 v174, v24, v24
	v_add_f32_e32 v173, v174, v173
	v_mul_f32_e32 v174, v27, v27
	v_fmac_f32_e32 v174, v26, v26
	v_add_f32_e32 v173, v174, v173
	v_mul_f32_e32 v174, v83, v83
	v_mul_f32_e32 v175, v85, v85
	v_fmac_f32_e32 v174, v82, v82
	v_fmac_f32_e32 v175, v84, v84
	v_add_f32_e32 v174, v174, v175
	v_mul_f32_e32 v175, v75, v75
	v_fmac_f32_e32 v175, v74, v74
	v_add_f32_e32 v174, v175, v174
	v_mul_f32_e32 v175, v77, v77
	v_fmac_f32_e32 v175, v76, v76
	v_add_f32_e32 v174, v175, v174
	v_mul_f32_e32 v175, v21, v21
	v_mul_f32_e32 v176, v23, v23
	v_fmac_f32_e32 v175, v20, v20
	v_fmac_f32_e32 v176, v22, v22
	v_add_f32_e32 v175, v175, v176
	v_mul_f32_e32 v176, v17, v17
	v_fmac_f32_e32 v176, v16, v16
	v_add_f32_e32 v175, v176, v175
	v_mul_f32_e32 v176, v19, v19
	v_fmac_f32_e32 v176, v18, v18
	v_add_f32_e32 v175, v176, v175
	v_mul_f32_e32 v176, v67, v67
	v_mul_f32_e32 v177, v69, v69
	v_fmac_f32_e32 v176, v66, v66
	v_fmac_f32_e32 v177, v68, v68
	v_add_f32_e32 v176, v176, v177
	v_mul_f32_e32 v177, v59, v59
	v_fmac_f32_e32 v177, v58, v58
	v_add_f32_e32 v158, v159, v158
	v_add_f32_e32 v176, v177, v176
	v_mul_f32_e32 v177, v61, v61
	v_mov_b32_e32 v159, v158
	v_fmac_f32_e32 v177, v60, v60
	s_nop 1
	v_permlane16_swap_b32 v159, v158
	s_nop 1
	v_add_f32_e32 v176, v177, v176
	v_mul_f32_e32 v177, v13, v13
	v_mul_f32_e32 v178, v15, v15
	v_add_f32_e32 v158, v159, v158
	v_add_f32_e32 v160, v161, v160
	v_fmac_f32_e32 v177, v12, v12
	v_fmac_f32_e32 v178, v14, v14
	v_mov_b32_e32 v159, v158
	v_mov_b32_e32 v161, v160
	v_add_f32_e32 v177, v177, v178
	v_mul_f32_e32 v178, v9, v9
	s_nop 1
	v_permlane32_swap_b32 v159, v158
	s_nop 1
	s_nop 1
	v_permlane16_swap_b32 v161, v160
	s_nop 1
	v_fmac_f32_e32 v178, v8, v8
	v_add_f32_e32 v160, v161, v160
	v_add_f32_e32 v162, v163, v162
	v_add_f32_e32 v177, v178, v177
	v_mul_f32_e32 v178, v11, v11
	v_mov_b32_e32 v161, v160
	v_mov_b32_e32 v163, v162
	v_fmac_f32_e32 v178, v10, v10
	s_nop 1
	v_permlane32_swap_b32 v161, v160
	s_nop 1
	s_nop 1
	v_permlane16_swap_b32 v163, v162
	s_nop 1
	v_add_f32_e32 v177, v178, v177
	v_mul_f32_e32 v178, v47, v47
	v_mul_f32_e32 v179, v49, v49
	v_add_f32_e32 v162, v163, v162
	v_add_f32_e32 v164, v165, v164
	v_fmac_f32_e32 v178, v46, v46
	v_fmac_f32_e32 v179, v48, v48
	v_mov_b32_e32 v163, v162
	v_mov_b32_e32 v165, v164
	v_add_f32_e32 v178, v178, v179
	v_mul_f32_e32 v179, v39, v39
	s_nop 1
	v_permlane32_swap_b32 v163, v162
	s_nop 1
	s_nop 1
	v_permlane16_swap_b32 v165, v164
	s_nop 1
	v_fmac_f32_e32 v179, v38, v38
	v_add_f32_e32 v164, v165, v164
	v_add_f32_e32 v172, v173, v172
	v_add_f32_e32 v178, v179, v178
	v_mul_f32_e32 v179, v41, v41
	v_mov_b32_e32 v165, v164
	v_mov_b32_e32 v173, v172
	v_fmac_f32_e32 v179, v40, v40
	s_nop 1
	v_permlane32_swap_b32 v165, v164
	s_nop 1
	s_nop 1
	v_permlane16_swap_b32 v173, v172
	s_nop 1
	v_add_f32_e32 v178, v179, v178
	v_mul_f32_e32 v179, v5, v5
	v_mul_f32_e32 v180, v7, v7
	v_add_f32_e32 v172, v173, v172
	v_add_f32_e32 v174, v175, v174
	v_fmac_f32_e32 v179, v4, v4
	v_fmac_f32_e32 v180, v6, v6
	v_mov_b32_e32 v173, v172
	v_mov_b32_e32 v175, v174
	v_add_f32_e32 v179, v179, v180
	v_mul_f32_e32 v180, v1, v1
	s_nop 1
	v_permlane32_swap_b32 v173, v172
	s_nop 1
	s_nop 1
	v_permlane16_swap_b32 v175, v174
	s_nop 1
	v_fmac_f32_e32 v180, v0, v0
	v_add_f32_e32 v174, v175, v174
	v_add_f32_e32 v176, v177, v176
	v_add_f32_e32 v179, v180, v179
	v_mul_f32_e32 v180, v3, v3
	v_mov_b32_e32 v175, v174
	v_mov_b32_e32 v177, v176
	v_fmac_f32_e32 v180, v2, v2
	s_nop 1
	v_permlane32_swap_b32 v175, v174
	s_nop 1
	s_nop 1
	v_permlane16_swap_b32 v177, v176
	s_nop 1
	v_add_f32_e32 v179, v180, v179
	v_add_f32_e32 v176, v177, v176
	v_add_f32_e32 v178, v179, v178
	v_mov_b32_e32 v177, v176
	v_mov_b32_e32 v179, v178
	s_nop 1
	v_permlane32_swap_b32 v177, v176
	s_nop 1
	s_nop 1
	v_permlane16_swap_b32 v179, v178
	s_nop 1
	s_nop 0
	v_add_f32_e32 v178, v179, v178
	v_mov_b32_e32 v179, v178
	s_nop 1
	v_permlane32_swap_b32 v179, v178
	s_nop 1
	s_and_saveexec_b64 s[8:9], s[6:7]
	s_cbranch_execz .LBB0_1752
	s_waitcnt vmcnt(0)
	v_add_f32_e32 v248, 1.0, v248
	v_mul_f32_e32 v154, v248, v245
	v_mul_f32_e32 v155, v246, v244
	v_mov_b32_e32 v35, v247
	v_lshl_add_u32 v180, v32, 2, 0
	ds_write2st64_b32 v180, v155, v154 offset0:24 offset1:28
	ds_write_b32 v180, v35 offset:8192
